# phase-6 output stores deferred: parked in registers and issued after the next tile's first LDS-DMA loads (vmcnt(8)), flushed at loop exit
# speedup vs baseline: 1.0170x; 1.0015x over previous
; DI int TIDX() { int t = threadIdx.x; asm volatile("" : "+v"(t)); return t; }
; DI int BIDX() { int b = blockIdx.x; asm volatile("" : "+s"(b)); return b; }
; DI int tile_groups(int MT, int NT) { return (MT >> 6) * ((NT + 7) >> 3) * 512; }
; template <int VAR> DI void phase_up(const Params& P, int l, char* smem) {
;   char* ws = P.ws;
;   const bf16_t* xb = (const bf16_t*)(ws + OFF_XB);
;   const bf16_t* Wt = (const bf16_t*)(ws + OFF_W) + (size_t)l * W_LAYER + WO_UP;
;   bf16_t* U = (bf16_t*)(ws + OFF_P);
;   const float* ssq = (const float*)(ws + OFF_SSQ) + (size_t)1 * NTOK * 16;
;   const int tid = TIDX(), lane = tid & 63, wid = tid >> 6, wm = wid >> 1, wn = wid & 1, lr = lane & 15, g = lane >> 4;
;   for (int vb = BIDX(); vb < tile_groups(128, 32); vb += gridDim.x) {
;     int tm, tn; if (!tile_of(vb, 128, 32, tm, tn)) continue;
;     const int m0 = tm * 128, n0 = tn * 128;
;     const int row0 = m0 + wm * 64, col0 = n0 + wn * 64;
.LBB0_1310:
	s_or_b64 exec, exec, s[4:5]
	s_waitcnt lgkmcnt(0)
	v_mov_b32_e32 v0, v148
	v_readlane_b32 s2, v253, 0
	s_barrier
	s_mov_b32 s100, 0
	s_cmpk_gt_i32 s2, 0xfff
	s_cbranch_scc1 .LBB0_1315
	v_readlane_b32 s1, v252, 19
	s_add_u32 s10, s1, 0x14c0000
	v_readlane_b32 s1, v252, 20
	v_and_b32_e32 v124, 64, v0
	v_and_b32_e32 v1, 15, v0
	v_ashrrev_i32_e32 v2, 1, v0
	v_lshrrev_b32_e32 v0, 1, v0
	s_addc_u32 s11, s1, 0
	v_and_b32_e32 v150, 24, v0
	s_movk_i32 s1, 0xffc0
	v_lshl_add_u64 v[96:97], s[34:35], 0, v[150:151]
	v_and_or_b32 v125, v2, s1, v1
	s_lshl_b32 s12, s2, 3
	s_branch .LBB0_1313

; DI int BIDX() { int b = blockIdx.x; asm volatile("" : "+s"(b)); return b; }
; DI int tile_groups(int MT, int NT) { return (MT >> 6) * ((NT + 7) >> 3) * 512; }
; DI void load_rstd(float (&rs)[4], const float* ssq, int row0, int lr) {
; #pragma unroll
;   for (int mt = 0; mt < 4; ++mt) {
;     const float4* q = (const float4*)(ssq + (size_t)(row0 + mt * 16 + lr) * 16);
;     const float4 a = q[0], b = q[1], c = q[2], d = q[3];
;     const float s = ((a.x + a.y) + (a.z + a.w)) + ((b.x + b.y) + (b.z + b.w)) + ((c.x + c.y) + (c.z + c.w)) + ((d.x + d.y) + (d.z + d.w));
;     rs[mt] = rsqrtf(s * (1.0f / 1024.0f) + EPS);
;   }
; }
; template <int VAR> DI void phase_up(const Params& P, int l, char* smem) {
;     ...
;   for (int vb = BIDX(); vb < tile_groups(128, 32); vb += gridDim.x) {
;     int tm, tn; if (!tile_of(vb, 128, 32, tm, tn)) continue;
;     const int m0 = tm * 128, n0 = tn * 128;
;     const int row0 = m0 + wm * 64, col0 = n0 + wn * 64;
;     f32x4 acc[4][4]; zero_acc(acc);
;     float rs[4]; load_rstd(rs, ssq, row0, lr);
.LBB0_1313:
	s_ashr_i32 s4, s2, 9
	s_lshr_b32 s1, s4, 30
	s_add_i32 s1, s4, s1
	s_ashr_i32 s5, s1, 2
	s_lshl_b32 s1, s5, 6
	s_and_b32 s6, s12, 56
	s_lshl_b32 s5, s5, 5
	s_lshl_b32 s4, s4, 3
	s_or_b32 s1, s1, s6
	s_bfe_u32 s6, s2, 0x30003
	s_sub_i32 s4, s4, s5
	s_bfe_u32 s5, s2, 0x30006
	s_or_b32 s1, s1, s6
	s_or_b32 s4, s4, s5
	s_cmpk_lt_i32 s1, 0x80
	s_cselect_b64 s[6:7], -1, 0
	s_cmp_lt_i32 s4, 32
	s_cselect_b64 s[8:9], -1, 0
	s_and_b64 s[6:7], s[6:7], s[8:9]
	s_andn2_b64 vcc, exec, s[6:7]
	s_cbranch_vccnz .LBB0_1312
	s_lshl_b32 s8, s1, 7
	v_add_u32_e32 v102, s8, v125
	v_ashrrev_i32_e32 v103, 31, v102
	v_readlane_b32 s14, v254, 41
	v_readlane_b32 s15, v254, 42
	v_or_b32_e32 v98, 16, v102
	v_ashrrev_i32_e32 v99, 31, v98
	s_lshl_b32 s6, s4, 7
	s_mov_b32 s4, 0x358637bd
	s_mov_b32 s16, 0x3a800000
	s_mov_b32 s1, 0x800000
	v_or_b32_e32 v106, 32, v102
	v_ashrrev_i32_e32 v107, 31, v106
	v_or_b32_e32 v104, 48, v102
	v_ashrrev_i32_e32 v105, 31, v104
	s_ashr_i32 s9, s8, 31
	v_and_b32_e32 v22, 48, v148
	v_mov_b32_e32 v23, 0
	v_mov_b32_e32 v21, s4
	v_lshlrev_b64 v[0:1], 6, v[102:103]
	v_lshl_add_u64 v[0:1], s[14:15], 0, v[0:1]
	v_lshl_add_u64 v[0:1], v[22:23], 0, v[0:1]
	v_lshlrev_b64 v[2:3], 6, v[98:99]
	v_lshl_add_u64 v[2:3], s[14:15], 0, v[2:3]
	v_lshl_add_u64 v[2:3], v[22:23], 0, v[2:3]
	v_lshlrev_b64 v[4:5], 6, v[106:107]
	v_lshl_add_u64 v[4:5], s[14:15], 0, v[4:5]
	v_lshl_add_u64 v[4:5], v[22:23], 0, v[4:5]
	v_lshlrev_b64 v[6:7], 6, v[104:105]
	v_lshl_add_u64 v[6:7], s[14:15], 0, v[6:7]
	v_lshl_add_u64 v[6:7], v[22:23], 0, v[6:7]
	global_load_dwordx4 v[8:11], v[0:1], off
	global_load_dwordx4 v[12:15], v[2:3], off
	global_load_dwordx4 v[16:19], v[4:5], off
	global_load_dwordx4 v[0:3], v[6:7], off
	s_waitcnt vmcnt(0)
	v_add_f32_e32 v8, v8, v9
	v_add_f32_e32 v10, v10, v11
	v_add_f32_e32 v8, v8, v10
	v_add_f32_e32 v12, v12, v13
	v_add_f32_e32 v14, v14, v15
	v_add_f32_e32 v12, v12, v14
	v_add_f32_e32 v16, v16, v17
	v_add_f32_e32 v18, v18, v19
	v_add_f32_e32 v16, v16, v18
	v_add_f32_e32 v0, v0, v1
	v_add_f32_e32 v2, v2, v3
	v_add_f32_e32 v0, v0, v2
	v_mov_b32_e32 v9, v8
	s_nop 1
	v_permlane16_swap_b32_e32 v8, v9
	v_mov_b32_e32 v10, v8
	v_mov_b32_e32 v11, v9
	s_nop 1
	v_permlane32_swap_b32_e32 v8, v10
	v_permlane32_swap_b32_e32 v9, v11
	v_add_f32_e32 v8, v8, v9
	v_add_f32_e32 v8, v8, v10
	v_add_f32_e32 v8, v8, v11
	v_fma_f32 v8, v8, s16, v21
	v_mov_b32_e32 v13, v12
	s_nop 1
	v_permlane16_swap_b32_e32 v12, v13
	v_mov_b32_e32 v14, v12
	v_mov_b32_e32 v15, v13
	s_nop 1
	v_permlane32_swap_b32_e32 v12, v14
	v_permlane32_swap_b32_e32 v13, v15
	v_add_f32_e32 v12, v12, v13
	v_add_f32_e32 v12, v12, v14
	v_add_f32_e32 v12, v12, v15
	v_fma_f32 v12, v12, s16, v21
	v_mov_b32_e32 v17, v16
	s_nop 1
	v_permlane16_swap_b32_e32 v16, v17
	v_mov_b32_e32 v18, v16
	v_mov_b32_e32 v19, v17
	s_nop 1
	v_permlane32_swap_b32_e32 v16, v18
	v_permlane32_swap_b32_e32 v17, v19
	v_add_f32_e32 v16, v16, v17
	v_add_f32_e32 v16, v16, v18
	v_add_f32_e32 v16, v16, v19
	v_fma_f32 v16, v16, s16, v21
	v_mov_b32_e32 v1, v0
	s_nop 1
	v_permlane16_swap_b32_e32 v0, v1
	v_mov_b32_e32 v2, v0
	v_mov_b32_e32 v3, v1
	s_nop 1
	v_permlane32_swap_b32_e32 v0, v2
	v_permlane32_swap_b32_e32 v1, v3
	v_add_f32_e32 v0, v0, v1
	v_add_f32_e32 v0, v0, v2
	v_add_f32_e32 v0, v0, v3
	v_fma_f32 v0, v0, s16, v21
	v_mul_f32_e32 v9, 0x4b800000, v8
	v_cmp_gt_f32_e32 vcc, s1, v8
	s_nop 1
	v_cndmask_b32_e32 v8, v8, v9, vcc
	v_rsq_f32_e32 v8, v8
	s_nop 0
	v_mul_f32_e32 v9, 0x45800000, v8
	v_cndmask_b32_e32 v128, v8, v9, vcc
	v_mul_f32_e32 v13, 0x4b800000, v12
	v_cmp_gt_f32_e32 vcc, s1, v12
	s_nop 1
	v_cndmask_b32_e32 v12, v12, v13, vcc
	v_rsq_f32_e32 v12, v12
	s_nop 0
	v_mul_f32_e32 v13, 0x45800000, v12
	v_cndmask_b32_e32 v126, v12, v13, vcc
	v_mul_f32_e32 v17, 0x4b800000, v16
	v_cmp_gt_f32_e32 vcc, s1, v16
	s_nop 1
	v_cndmask_b32_e32 v16, v16, v17, vcc
	v_rsq_f32_e32 v16, v16
	s_nop 0
	v_mul_f32_e32 v17, 0x45800000, v16
	v_cndmask_b32_e32 v129, v16, v17, vcc
	v_mul_f32_e32 v1, 0x4b800000, v0
	v_cmp_gt_f32_e32 vcc, s1, v0
	s_nop 1
	v_cndmask_b32_e32 v0, v0, v1, vcc
	v_rsq_f32_e32 v0, v0
	s_nop 0
	v_mul_f32_e32 v1, 0x45800000, v0
	v_cndmask_b32_e32 v127, v0, v1, vcc
	v_mov_b32_e32 v72, v148
	v_or_b32_e32 v100, s6, v124
	v_ashrrev_i32_e32 v64, 3, v72
	v_ashrrev_i32_e32 v65, 31, v64
	v_and_b32_e32 v75, 48, v72
	v_lshlrev_b64 v[16:17], 11, v[64:65]
	v_lshlrev_b32_e32 v65, 4, v72
	v_and_b32_e32 v150, 0x70, v65
	v_add_u32_e32 v66, 32, v64
	s_lshl_b64 s[4:5], s[8:9], 11
	v_readlane_b32 s8, v254, 43
	v_readlane_b32 s9, v254, 44
	s_add_u32 s4, s8, s4
	s_addc_u32 s5, s9, s5
	v_lshlrev_b32_e32 v0, 3, v72
	s_ashr_i32 s7, s6, 31
	v_and_b32_e32 v74, 0x70, v0
	v_bitop3_b32 v134, v0, v75, s23 bitop3:0x6c
	v_lshl_add_u64 v[0:1], s[4:5], 0, v[16:17]
	v_add_u32_e32 v68, 64, v64
	v_add_u32_e32 v70, 0x60, v64
	s_lshl_b64 s[6:7], s[6:7], 11
	v_lshl_add_u64 v[108:109], v[0:1], 0, v[150:151]
	v_ashrrev_i32_e32 v67, 31, v66
	v_ashrrev_i32_e32 v69, 31, v68
	v_ashrrev_i32_e32 v71, 31, v70
	s_add_u32 s6, s10, s6
	v_lshlrev_b64 v[20:21], 11, v[66:67]
	v_lshlrev_b64 v[24:25], 11, v[68:69]
	v_lshlrev_b64 v[28:29], 11, v[70:71]
	s_addc_u32 s7, s11, s7
	v_lshl_add_u64 v[4:5], s[4:5], 0, v[20:21]
	v_lshl_add_u64 v[8:9], s[4:5], 0, v[24:25]
	v_lshl_add_u64 v[12:13], s[4:5], 0, v[28:29]
	v_lshl_add_u64 v[110:111], v[4:5], 0, v[150:151]
	v_lshl_add_u64 v[112:113], v[8:9], 0, v[150:151]
	v_lshl_add_u64 v[114:115], v[12:13], 0, v[150:151]
	v_lshl_add_u64 v[16:17], s[6:7], 0, v[16:17]
	v_lshl_add_u64 v[116:117], v[16:17], 0, v[150:151]
	v_lshl_add_u64 v[20:21], s[6:7], 0, v[20:21]
	v_lshl_add_u64 v[118:119], v[20:21], 0, v[150:151]
	v_lshl_add_u64 v[24:25], s[6:7], 0, v[24:25]
; DI int TIDX() { int t = threadIdx.x; asm volatile("" : "+v"(t)); return t; }
; #define GL_LOAD(s_, kt_) if (VAR != 1) { a##s_##0 = GL_A(0, kt_); a##s_##1 = GL_A(1, kt_); a##s_##2 = GL_A(2, kt_); a##s_##3 = GL_A(3, kt_); b##s_##0 = GL_B(0, kt_); b##s_##1 = GL_B(1, kt_); b##s_##2 = GL_B(2, kt_); b##s_##3 = GL_B(3, kt_); }
; #define LDS_STORE(s_, buf_) if (VAR != 2) { LDS_ST1(sA, 0, buf_, a##s_##0) LDS_ST1(sA, 1, buf_, a##s_##1) LDS_ST1(sA, 2, buf_, a##s_##2) LDS_ST1(sA, 3, buf_, a##s_##3) LDS_ST1(sB, 0, buf_, b##s_##0) LDS_ST1(sB, 1, buf_, b##s_##1) LDS_ST1(sB, 2, buf_, b##s_##2) LDS_ST1(sB, 3, buf_, b##s_##3) }
;   const int tid = TIDX(), lane = tid & 63, wid = tid >> 6, wm = wid >> 1, wn = wid & 1, lr = lane & 15, g = lane >> 4;
;   char* sA = smem; char* sB = smem + 2 * LTILE;
;   uint4 a00 = {}, a01 = {}, a02 = {}, a03 = {}, b00 = {}, b01 = {}, b02 = {}, b03 = {}, a10 = {}, a11 = {}, a12 = {}, a13 = {}, b10 = {}, b11 = {}, b12 = {}, b13 = {};
;   constexpr int nk = NK;
;   const int sw0 = (g ^ ((lr >> 1) & 7)) << 4, sw1 = sw0 ^ 64;
;   const int r0 = tid >> 3, kc = tid & 7, kcs = kc ^ ((r0 >> 1) & 7);
;     ...
;   GL_LOAD(0, 0)
;   GL_LOAD(1, 1)
;   LDS_STORE(0, 0)
;   if (VAR != 4) __syncthreads();
	v_lshl_add_u64 v[120:121], v[24:25], 0, v[150:151]
	v_lshl_add_u64 v[28:29], s[6:7], 0, v[28:29]
	v_lshl_add_u64 v[122:123], v[28:29], 0, v[150:151]
	v_bitop3_b32 v65, v65, s23, v72 bitop3:0x48
	v_lshl_or_b32 v101, v64, 7, v65
	v_and_b32_e32 v73, 15, v72
	v_lshl_or_b32 v131, v66, 7, v65
	v_lshl_or_b32 v132, v68, 7, v65
	v_lshl_or_b32 v130, v70, 7, v65
	v_xor_b32_e32 v135, 64, v134
	v_writelane_b32 v255, s60, 0
	v_writelane_b32 v255, s61, 1
	v_writelane_b32 v255, s62, 2
	v_writelane_b32 v255, s63, 3
	v_writelane_b32 v255, s64, 4
	v_writelane_b32 v255, s65, 5
	v_writelane_b32 v255, s66, 6
	v_writelane_b32 v255, s67, 7
	v_writelane_b32 v255, s68, 8
	v_writelane_b32 v255, s69, 9
	v_writelane_b32 v255, s70, 10
	v_writelane_b32 v255, s71, 11
	v_writelane_b32 v255, s72, 12
	v_writelane_b32 v255, s73, 13
	v_writelane_b32 v255, s74, 14
	v_writelane_b32 v255, s75, 15
	v_mov_b32_e32 v3, v101
	v_and_b32_e32 v3, 0xffffff80, v3
	s_nop 0
	v_readfirstlane_b32 s60, v3
	v_add_u32_e32 v3, 0x4000, v101
	v_and_b32_e32 v3, 0xffffff80, v3
	s_nop 0
	v_readfirstlane_b32 s61, v3
	v_add_u32_e32 v3, 0x8000, v101
	v_and_b32_e32 v3, 0xffffff80, v3
	s_nop 0
	v_readfirstlane_b32 s62, v3
	v_add_u32_e32 v3, 0xc000, v101
	v_and_b32_e32 v3, 0xffffff80, v3
	s_nop 0
	v_readfirstlane_b32 s63, v3
	v_mov_b32_e32 v3, v130
	v_and_b32_e32 v3, 0xffffff80, v3
	s_nop 0
	v_readfirstlane_b32 s64, v3
	v_add_u32_e32 v3, 0x4000, v130
	v_and_b32_e32 v3, 0xffffff80, v3
	s_nop 0
	v_readfirstlane_b32 s65, v3
	v_add_u32_e32 v3, 0x8000, v130
	v_and_b32_e32 v3, 0xffffff80, v3
	s_nop 0
	v_readfirstlane_b32 s66, v3
	v_add_u32_e32 v3, 0xc000, v130
	v_and_b32_e32 v3, 0xffffff80, v3
	s_nop 0
	v_readfirstlane_b32 s67, v3
	v_mov_b32_e32 v3, v131
	v_and_b32_e32 v3, 0xffffff80, v3
	s_nop 0
	v_readfirstlane_b32 s68, v3
	v_add_u32_e32 v3, 0x4000, v131
	v_and_b32_e32 v3, 0xffffff80, v3
	s_nop 0
	v_readfirstlane_b32 s69, v3
	v_add_u32_e32 v3, 0x8000, v131
	v_and_b32_e32 v3, 0xffffff80, v3
	s_nop 0
	v_readfirstlane_b32 s70, v3
	v_add_u32_e32 v3, 0xc000, v131
	v_and_b32_e32 v3, 0xffffff80, v3
	s_nop 0
	v_readfirstlane_b32 s71, v3
	v_mov_b32_e32 v3, v132
	v_and_b32_e32 v3, 0xffffff80, v3
	s_nop 0
	v_readfirstlane_b32 s72, v3
	v_add_u32_e32 v3, 0x4000, v132
	v_and_b32_e32 v3, 0xffffff80, v3
	s_nop 0
	v_readfirstlane_b32 s73, v3
	v_add_u32_e32 v3, 0x8000, v132
	v_and_b32_e32 v3, 0xffffff80, v3
	s_nop 0
	v_readfirstlane_b32 s74, v3
	v_add_u32_e32 v3, 0xc000, v132
	v_and_b32_e32 v3, 0xffffff80, v3
	s_nop 0
	v_readfirstlane_b32 s75, v3
	v_and_b32_e32 v30, 7, v148
	v_bfe_u32 v31, v148, 4, 3
	v_xor_b32_e32 v31, v31, v30
	v_sub_u32_e32 v31, v31, v30
	v_lshlrev_b32_e32 v30, 4, v31
	v_ashrrev_i32_e32 v31, 31, v30
	v_lshl_add_u64 v[0:1], v[108:109], 0, v[30:31]
	s_mov_b32 m0, s60
	s_nop 0
	global_load_lds_dwordx4 v[0:1], off
	v_lshrrev_b32_e32 v0, 1, v72
	v_and_or_b32 v0, v0, s24, v73
	v_lshlrev_b32_e32 v137, 7, v0
	v_lshlrev_b32_e32 v0, 7, v72
	v_and_b32_e32 v146, 0x2780, v0
	v_bitop3_b32 v133, v137, v74, v75 bitop3:0xf6
	v_or_b32_e32 v136, v146, v134
	v_bitop3_b32 v134, v137, v134, 64 bitop3:0xf6
	v_or_b32_e32 v135, v146, v135
	v_lshl_add_u64 v[4:5], v[110:111], 0, v[30:31]
	s_mov_b32 m0, s68
	s_nop 0
	global_load_lds_dwordx4 v[4:5], off
	v_lshl_add_u64 v[8:9], v[112:113], 0, v[30:31]
	s_mov_b32 m0, s72
	s_nop 0
	global_load_lds_dwordx4 v[8:9], off
	v_lshl_add_u64 v[12:13], v[114:115], 0, v[30:31]
	s_mov_b32 m0, s64
	s_nop 0
	global_load_lds_dwordx4 v[12:13], off
	v_lshl_add_u64 v[16:17], v[116:117], 0, v[30:31]
	s_mov_b32 m0, s62
	s_nop 0
	global_load_lds_dwordx4 v[16:17], off
	v_lshl_add_u64 v[20:21], v[118:119], 0, v[30:31]
	s_mov_b32 m0, s70
	s_nop 0
	global_load_lds_dwordx4 v[20:21], off
	v_lshl_add_u64 v[24:25], v[120:121], 0, v[30:31]
	s_mov_b32 m0, s74
	s_nop 0
	global_load_lds_dwordx4 v[24:25], off
	v_lshl_add_u64 v[28:29], v[122:123], 0, v[30:31]
	s_mov_b32 m0, s66
	s_nop 0
	global_load_lds_dwordx4 v[28:29], off
	s_cmp_eq_u32 s100, 0
	s_cbranch_scc1 .Lp6d_none
	global_store_dwordx4 v[154:155], v[44:47], off
	global_store_dwordx4 v[156:157], v[48:51], off
	global_store_dwordx4 v[158:159], v[52:55], off
	global_store_dwordx4 v[160:161], v[56:59], off
	global_store_dwordx4 v[162:163], v[60:63], off
	global_store_dwordx4 v[164:165], v[32:35], off
	global_store_dwordx4 v[166:167], v[36:39], off
	global_store_dwordx4 v[168:169], v[40:43], off
	s_mov_b32 s100, 0
	s_waitcnt lgkmcnt(0)
	s_waitcnt vmcnt(8)
	s_branch .Lp6d_join
.Lp6d_none:
	s_waitcnt lgkmcnt(0)
	s_waitcnt vmcnt(0)
; #define GL_LOAD(s_, kt_) if (VAR != 1) { a##s_##0 = GL_A(0, kt_); a##s_##1 = GL_A(1, kt_); a##s_##2 = GL_A(2, kt_); a##s_##3 = GL_A(3, kt_); b##s_##0 = GL_B(0, kt_); b##s_##1 = GL_B(1, kt_); b##s_##2 = GL_B(2, kt_); b##s_##3 = GL_B(3, kt_); }
; #define LDS_STORE(s_, buf_) if (VAR != 2) { LDS_ST1(sA, 0, buf_, a##s_##0) LDS_ST1(sA, 1, buf_, a##s_##1) LDS_ST1(sA, 2, buf_, a##s_##2) LDS_ST1(sA, 3, buf_, a##s_##3) LDS_ST1(sB, 0, buf_, b##s_##0) LDS_ST1(sB, 1, buf_, b##s_##1) LDS_ST1(sB, 2, buf_, b##s_##2) LDS_ST1(sB, 3, buf_, b##s_##3) }
;     ...
;   GL_LOAD(0, 0)
;   GL_LOAD(1, 1)
;   LDS_STORE(0, 0)
;   if (VAR != 4) __syncthreads();
; #pragma unroll
;   for (int kt = 0; kt < nk; kt += 2) {
;     if (kt + 2 < nk) { GL_LOAD(0, kt + 2) }
;     MMA_TILE(0)
;     LDS_STORE(1, 1)
;     if (VAR != 4) __syncthreads();
;     if (kt + 3 < nk) { GL_LOAD(1, kt + 3) }
;     MMA_TILE(1)
.Lp6d_join:
	s_barrier
	s_setprio 1
	ds_read_b128 v[64:67], v133
	ds_read_b128 v[68:71], v136 offset:32768
	s_waitcnt lgkmcnt(0)
	v_mfma_f32_16x16x32_f16 v[138:141], v[68:71], v[64:67], 0
	ds_read_b128 v[72:75], v133 offset:2048
	ds_read_b128 v[76:79], v136 offset:34816
	s_waitcnt lgkmcnt(1)
	v_mfma_f32_16x16x32_f16 v[158:161], v[68:71], v[72:75], 0
	ds_read_b128 v[80:83], v133 offset:4096
	ds_read_b128 v[84:87], v136 offset:36864
	s_waitcnt lgkmcnt(2)
	v_mfma_f32_16x16x32_f16 v[142:145], v[76:79], v[64:67], 0
	ds_read_b128 v[88:91], v133 offset:6144
	ds_read_b128 v[92:95], v136 offset:38912
	v_mfma_f32_16x16x32_f16 v[162:165], v[76:79], v[72:75], 0
	ds_read_b128 v[202:205], v135 offset:32768
	ds_read_b128 v[206:209], v134 offset:2048
	s_waitcnt lgkmcnt(5)
	v_mfma_f32_16x16x32_f16 v[190:193], v[68:71], v[80:83], 0
	ds_read_b128 v[210:213], v135 offset:34816
	ds_read_b128 v[220:223], v134 offset:4096
	s_waitcnt lgkmcnt(5)
	v_mfma_f32_16x16x32_f16 v[68:71], v[68:71], v[88:91], 0
	ds_read_b128 v[224:227], v135 offset:36864
	v_mfma_f32_16x16x32_f16 v[194:197], v[76:79], v[80:83], 0
	ds_read_b128 v[228:231], v134 offset:6144
	v_mfma_f32_16x16x32_f16 v[76:79], v[76:79], v[88:91], 0
	ds_read_b128 v[232:235], v135 offset:38912
	v_mfma_f32_16x16x32_f16 v[154:157], v[84:87], v[64:67], 0
	v_mfma_f32_16x16x32_f16 v[166:169], v[84:87], v[72:75], 0
	s_waitcnt lgkmcnt(7)
	v_mfma_f32_16x16x32_f16 v[64:67], v[92:95], v[64:67], 0
	v_mfma_f32_16x16x32_f16 v[72:75], v[92:95], v[72:75], 0
	v_mfma_f32_16x16x32_f16 v[198:201], v[84:87], v[80:83], 0
	v_and_b32_e32 v62, 7, v148
	v_bfe_u32 v63, v148, 4, 3
	v_xor_b32_e32 v63, v63, v62
	v_sub_u32_e32 v63, v63, v62
	v_lshlrev_b32_e32 v62, 4, v63
	v_add_u32_e32 v62, 0x80, v62
	v_ashrrev_i32_e32 v63, 31, v62
	v_mfma_f32_16x16x32_f16 v[84:87], v[84:87], v[88:91], 0
	v_lshl_add_u64 v[32:33], v[108:109], 0, v[62:63]
	s_mov_b32 m0, s61
	s_nop 0
	global_load_lds_dwordx4 v[32:33], off
	v_lshl_add_u64 v[36:37], v[110:111], 0, v[62:63]
	s_mov_b32 m0, s69
	s_nop 0
	global_load_lds_dwordx4 v[36:37], off
	v_mfma_f32_16x16x32_f16 v[80:83], v[92:95], v[80:83], 0
	v_lshl_add_u64 v[40:41], v[112:113], 0, v[62:63]
	s_mov_b32 m0, s73
	s_nop 0
	global_load_lds_dwordx4 v[40:41], off
	v_lshl_add_u64 v[44:45], v[114:115], 0, v[62:63]
	s_mov_b32 m0, s65
	s_nop 0
	global_load_lds_dwordx4 v[44:45], off
	v_mfma_f32_16x16x32_f16 v[88:91], v[92:95], v[88:91], 0
	ds_read_b128 v[92:95], v134
	v_lshl_add_u64 v[48:49], v[116:117], 0, v[62:63]
	s_mov_b32 m0, s63
	s_nop 0
	global_load_lds_dwordx4 v[48:49], off
	v_lshl_add_u64 v[52:53], v[118:119], 0, v[62:63]
	s_mov_b32 m0, s71
	s_nop 0
	global_load_lds_dwordx4 v[52:53], off
	v_lshl_add_u64 v[56:57], v[120:121], 0, v[62:63]
	s_mov_b32 m0, s75
	s_nop 0
	global_load_lds_dwordx4 v[56:57], off
	v_lshl_add_u64 v[60:61], v[122:123], 0, v[62:63]
	s_mov_b32 m0, s67
	s_nop 0
	global_load_lds_dwordx4 v[60:61], off
	s_waitcnt vmcnt(0) lgkmcnt(0)
	s_barrier
	v_mfma_f32_16x16x32_f16 v[138:141], v[202:205], v[92:95], v[138:141]
	v_mfma_f32_16x16x32_f16 v[142:145], v[210:213], v[92:95], v[142:145]
	v_mfma_f32_16x16x32_f16 v[154:157], v[224:227], v[92:95], v[154:157]
	v_mfma_f32_16x16x32_f16 v[64:67], v[232:235], v[92:95], v[64:67]
	v_mfma_f32_16x16x32_f16 v[92:95], v[202:205], v[206:209], v[158:161]
	v_mfma_f32_16x16x32_f16 v[158:161], v[210:213], v[206:209], v[162:165]
	v_mfma_f32_16x16x32_f16 v[162:165], v[224:227], v[206:209], v[166:169]
	v_mfma_f32_16x16x32_f16 v[166:169], v[202:205], v[220:223], v[190:193]
	v_mfma_f32_16x16x32_f16 v[68:71], v[202:205], v[228:231], v[68:71]
	ds_read_b128 v[202:205], v136 offset:49152
	v_mfma_f32_16x16x32_f16 v[190:193], v[210:213], v[220:223], v[194:197]
	v_mfma_f32_16x16x32_f16 v[76:79], v[210:213], v[228:231], v[76:79]
	ds_read_b128 v[210:213], v136 offset:51200
	v_and_b32_e32 v30, 7, v148
	v_bfe_u32 v31, v148, 4, 3
	v_xor_b32_e32 v31, v31, v30
	v_sub_u32_e32 v31, v31, v30
	v_lshlrev_b32_e32 v30, 4, v31
	v_add_u32_e32 v30, 0x100, v30
	v_ashrrev_i32_e32 v31, 31, v30
	v_mfma_f32_16x16x32_f16 v[72:75], v[232:235], v[206:209], v[72:75]
	ds_read_b128 v[206:209], v133 offset:18432
	v_mfma_f32_16x16x32_f16 v[194:197], v[224:227], v[220:223], v[198:201]
	s_nop 2
	ds_read_b128 v[198:201], v133 offset:16384
	v_mfma_f32_16x16x32_f16 v[84:87], v[224:227], v[228:231], v[84:87]
	ds_read_b128 v[224:227], v136 offset:53248
	v_mfma_f32_16x16x32_f16 v[80:83], v[232:235], v[220:223], v[80:83]
	ds_read_b128 v[220:223], v133 offset:20480
	v_mfma_f32_16x16x32_f16 v[88:91], v[232:235], v[228:231], v[88:91]
	ds_read_b128 v[228:231], v133 offset:22528
	s_waitcnt lgkmcnt(3)
	v_mfma_f32_16x16x32_f16 v[138:141], v[202:205], v[198:201], v[138:141]
	ds_read_b128 v[232:235], v136 offset:55296
	v_mfma_f32_16x16x32_f16 v[92:95], v[202:205], v[206:209], v[92:95]
	v_lshl_add_u64 v[0:1], v[108:109], 0, v[30:31]
	s_mov_b32 m0, s60
	s_nop 0
	global_load_lds_dwordx4 v[0:1], off
	v_mfma_f32_16x16x32_f16 v[142:145], v[210:213], v[198:201], v[142:145]
	v_lshl_add_u64 v[4:5], v[110:111], 0, v[30:31]
	s_mov_b32 m0, s68
	s_nop 0
	global_load_lds_dwordx4 v[4:5], off
	v_mfma_f32_16x16x32_f16 v[158:161], v[210:213], v[206:209], v[158:161]
	v_lshl_add_u64 v[8:9], v[112:113], 0, v[30:31]
	s_mov_b32 m0, s72
	s_nop 0
	global_load_lds_dwordx4 v[8:9], off
	s_waitcnt lgkmcnt(2)
	v_mfma_f32_16x16x32_f16 v[166:169], v[202:205], v[220:223], v[166:169]
	v_lshl_add_u64 v[12:13], v[114:115], 0, v[30:31]
	s_mov_b32 m0, s64
	s_nop 0
	global_load_lds_dwordx4 v[12:13], off
	s_waitcnt lgkmcnt(1)
; #define GL_LOAD(s_, kt_) if (VAR != 1) { a##s_##0 = GL_A(0, kt_); a##s_##1 = GL_A(1, kt_); a##s_##2 = GL_A(2, kt_); a##s_##3 = GL_A(3, kt_); b##s_##0 = GL_B(0, kt_); b##s_##1 = GL_B(1, kt_); b##s_##2 = GL_B(2, kt_); b##s_##3 = GL_B(3, kt_); }
; #define LDS_STORE(s_, buf_) if (VAR != 2) { LDS_ST1(sA, 0, buf_, a##s_##0) LDS_ST1(sA, 1, buf_, a##s_##1) LDS_ST1(sA, 2, buf_, a##s_##2) LDS_ST1(sA, 3, buf_, a##s_##3) LDS_ST1(sB, 0, buf_, b##s_##0) LDS_ST1(sB, 1, buf_, b##s_##1) LDS_ST1(sB, 2, buf_, b##s_##2) LDS_ST1(sB, 3, buf_, b##s_##3) }
;     ...
;   GL_LOAD(0, 0)
;   GL_LOAD(1, 1)
;   LDS_STORE(0, 0)
;   if (VAR != 4) __syncthreads();
; #pragma unroll
;   for (int kt = 0; kt < nk; kt += 2) {
;     if (kt + 2 < nk) { GL_LOAD(0, kt + 2) }
;     MMA_TILE(0)
;     LDS_STORE(1, 1)
;     if (VAR != 4) __syncthreads();
;     if (kt + 3 < nk) { GL_LOAD(1, kt + 3) }
;     MMA_TILE(1)
;     if (kt + 2 < nk) { LDS_STORE(0, 0) }
;     if (VAR != 4) __syncthreads();
	v_mfma_f32_16x16x32_f16 v[68:71], v[202:205], v[228:231], v[68:71]
	ds_read_b128 v[202:205], v135 offset:49152
	v_mfma_f32_16x16x32_f16 v[190:193], v[210:213], v[220:223], v[190:193]
	v_lshl_add_u64 v[16:17], v[116:117], 0, v[30:31]
	s_mov_b32 m0, s62
	s_nop 0
	global_load_lds_dwordx4 v[16:17], off
	v_mfma_f32_16x16x32_f16 v[76:79], v[210:213], v[228:231], v[76:79]
	ds_read_b128 v[210:213], v135 offset:51200
	v_mfma_f32_16x16x32_f16 v[154:157], v[224:227], v[198:201], v[154:157]
	v_lshl_add_u64 v[20:21], v[118:119], 0, v[30:31]
	s_mov_b32 m0, s70
	s_nop 0
	global_load_lds_dwordx4 v[20:21], off
	v_mfma_f32_16x16x32_f16 v[162:165], v[224:227], v[206:209], v[162:165]
	v_lshl_add_u64 v[24:25], v[120:121], 0, v[30:31]
	s_mov_b32 m0, s74
	s_nop 0
	global_load_lds_dwordx4 v[24:25], off
	s_waitcnt lgkmcnt(2)
	v_mfma_f32_16x16x32_f16 v[64:67], v[232:235], v[198:201], v[64:67]
	ds_read_b128 v[198:201], v134 offset:16384
	v_mfma_f32_16x16x32_f16 v[72:75], v[232:235], v[206:209], v[72:75]
	ds_read_b128 v[206:209], v134 offset:18432
	v_mfma_f32_16x16x32_f16 v[194:197], v[224:227], v[220:223], v[194:197]
	v_lshl_add_u64 v[28:29], v[122:123], 0, v[30:31]
	s_mov_b32 m0, s66
	s_nop 0
	global_load_lds_dwordx4 v[28:29], off
	v_mfma_f32_16x16x32_f16 v[84:87], v[224:227], v[228:231], v[84:87]
	ds_read_b128 v[224:227], v135 offset:53248
	v_mfma_f32_16x16x32_f16 v[80:83], v[232:235], v[220:223], v[80:83]
	ds_read_b128 v[220:223], v134 offset:20480
	v_mfma_f32_16x16x32_f16 v[88:91], v[232:235], v[228:231], v[88:91]
	ds_read_b128 v[228:231], v134 offset:22528
	ds_read_b128 v[232:235], v135 offset:55296
	s_waitcnt vmcnt(0) lgkmcnt(0)
	s_barrier
	v_mfma_f32_16x16x32_f16 v[138:141], v[202:205], v[198:201], v[138:141]
	v_mfma_f32_16x16x32_f16 v[92:95], v[202:205], v[206:209], v[92:95]
	v_mfma_f32_16x16x32_f16 v[142:145], v[210:213], v[198:201], v[142:145]
	v_mfma_f32_16x16x32_f16 v[158:161], v[210:213], v[206:209], v[158:161]
	v_mfma_f32_16x16x32_f16 v[166:169], v[202:205], v[220:223], v[166:169]
	v_mfma_f32_16x16x32_f16 v[68:71], v[202:205], v[228:231], v[68:71]
	ds_read_b128 v[202:205], v136 offset:32768
	v_mfma_f32_16x16x32_f16 v[190:193], v[210:213], v[220:223], v[190:193]
	v_mfma_f32_16x16x32_f16 v[76:79], v[210:213], v[228:231], v[76:79]
	ds_read_b128 v[210:213], v136 offset:34816
	v_mfma_f32_16x16x32_f16 v[154:157], v[224:227], v[198:201], v[154:157]
	v_mfma_f32_16x16x32_f16 v[162:165], v[224:227], v[206:209], v[162:165]
	v_mfma_f32_16x16x32_f16 v[64:67], v[232:235], v[198:201], v[64:67]
	ds_read_b128 v[198:201], v133
	v_mfma_f32_16x16x32_f16 v[72:75], v[232:235], v[206:209], v[72:75]
	ds_read_b128 v[206:209], v133 offset:2048
	v_mfma_f32_16x16x32_f16 v[194:197], v[224:227], v[220:223], v[194:197]
	v_and_b32_e32 v62, 7, v148
	v_bfe_u32 v63, v148, 4, 3
	v_xor_b32_e32 v63, v63, v62
	v_sub_u32_e32 v63, v63, v62
	v_lshlrev_b32_e32 v62, 4, v63
	v_add_u32_e32 v62, 0x180, v62
	v_ashrrev_i32_e32 v63, 31, v62
	v_mfma_f32_16x16x32_f16 v[84:87], v[224:227], v[228:231], v[84:87]
	ds_read_b128 v[224:227], v136 offset:36864
	v_mfma_f32_16x16x32_f16 v[80:83], v[232:235], v[220:223], v[80:83]
	ds_read_b128 v[220:223], v133 offset:4096
	v_mfma_f32_16x16x32_f16 v[88:91], v[232:235], v[228:231], v[88:91]
	ds_read_b128 v[228:231], v133 offset:6144
	s_waitcnt lgkmcnt(4)
	v_mfma_f32_16x16x32_f16 v[138:141], v[202:205], v[198:201], v[138:141]
	ds_read_b128 v[232:235], v136 offset:38912
	s_waitcnt lgkmcnt(4)
	v_mfma_f32_16x16x32_f16 v[92:95], v[202:205], v[206:209], v[92:95]
	v_lshl_add_u64 v[32:33], v[108:109], 0, v[62:63]
	s_mov_b32 m0, s61
	s_nop 0
	global_load_lds_dwordx4 v[32:33], off
	v_mfma_f32_16x16x32_f16 v[142:145], v[210:213], v[198:201], v[142:145]
	v_lshl_add_u64 v[36:37], v[110:111], 0, v[62:63]
	s_mov_b32 m0, s69
	s_nop 0
	global_load_lds_dwordx4 v[36:37], off
	v_mfma_f32_16x16x32_f16 v[158:161], v[210:213], v[206:209], v[158:161]
	v_lshl_add_u64 v[40:41], v[112:113], 0, v[62:63]
	s_mov_b32 m0, s73
	s_nop 0
	global_load_lds_dwordx4 v[40:41], off
	s_waitcnt lgkmcnt(2)
	v_mfma_f32_16x16x32_f16 v[166:169], v[202:205], v[220:223], v[166:169]
	v_lshl_add_u64 v[44:45], v[114:115], 0, v[62:63]
	s_mov_b32 m0, s65
	s_nop 0
	global_load_lds_dwordx4 v[44:45], off
	s_waitcnt lgkmcnt(1)
	v_mfma_f32_16x16x32_f16 v[68:71], v[202:205], v[228:231], v[68:71]
	ds_read_b128 v[202:205], v135 offset:32768
	v_mfma_f32_16x16x32_f16 v[190:193], v[210:213], v[220:223], v[190:193]
	v_lshl_add_u64 v[48:49], v[116:117], 0, v[62:63]
	s_mov_b32 m0, s63
	s_nop 0
	global_load_lds_dwordx4 v[48:49], off
	v_mfma_f32_16x16x32_f16 v[76:79], v[210:213], v[228:231], v[76:79]
	ds_read_b128 v[210:213], v135 offset:34816
	v_mfma_f32_16x16x32_f16 v[154:157], v[224:227], v[198:201], v[154:157]
	v_lshl_add_u64 v[52:53], v[118:119], 0, v[62:63]
	s_mov_b32 m0, s71
	s_nop 0
	global_load_lds_dwordx4 v[52:53], off
	v_mfma_f32_16x16x32_f16 v[162:165], v[224:227], v[206:209], v[162:165]
	v_lshl_add_u64 v[56:57], v[120:121], 0, v[62:63]
	s_mov_b32 m0, s75
	s_nop 0
	global_load_lds_dwordx4 v[56:57], off
	s_waitcnt lgkmcnt(2)
	v_mfma_f32_16x16x32_f16 v[64:67], v[232:235], v[198:201], v[64:67]
	ds_read_b128 v[198:201], v134
	v_mfma_f32_16x16x32_f16 v[72:75], v[232:235], v[206:209], v[72:75]
	ds_read_b128 v[206:209], v134 offset:2048
	v_mfma_f32_16x16x32_f16 v[194:197], v[224:227], v[220:223], v[194:197]
	v_lshl_add_u64 v[60:61], v[122:123], 0, v[62:63]
	s_mov_b32 m0, s67
	s_nop 0
	global_load_lds_dwordx4 v[60:61], off
	v_mfma_f32_16x16x32_f16 v[84:87], v[224:227], v[228:231], v[84:87]
	ds_read_b128 v[224:227], v135 offset:36864
	v_mfma_f32_16x16x32_f16 v[80:83], v[232:235], v[220:223], v[80:83]
	ds_read_b128 v[220:223], v134 offset:4096
	v_mfma_f32_16x16x32_f16 v[88:91], v[232:235], v[228:231], v[88:91]
	ds_read_b128 v[228:231], v134 offset:6144
	ds_read_b128 v[232:235], v135 offset:38912
	s_waitcnt vmcnt(0) lgkmcnt(0)
	s_barrier
; #define GL_LOAD(s_, kt_) if (VAR != 1) { a##s_##0 = GL_A(0, kt_); a##s_##1 = GL_A(1, kt_); a##s_##2 = GL_A(2, kt_); a##s_##3 = GL_A(3, kt_); b##s_##0 = GL_B(0, kt_); b##s_##1 = GL_B(1, kt_); b##s_##2 = GL_B(2, kt_); b##s_##3 = GL_B(3, kt_); }
; #define LDS_STORE(s_, buf_) if (VAR != 2) { LDS_ST1(sA, 0, buf_, a##s_##0) LDS_ST1(sA, 1, buf_, a##s_##1) LDS_ST1(sA, 2, buf_, a##s_##2) LDS_ST1(sA, 3, buf_, a##s_##3) LDS_ST1(sB, 0, buf_, b##s_##0) LDS_ST1(sB, 1, buf_, b##s_##1) LDS_ST1(sB, 2, buf_, b##s_##2) LDS_ST1(sB, 3, buf_, b##s_##3) }
;     ...
;   GL_LOAD(0, 0)
;   GL_LOAD(1, 1)
;   LDS_STORE(0, 0)
;   if (VAR != 4) __syncthreads();
; #pragma unroll
;   for (int kt = 0; kt < nk; kt += 2) {
;     if (kt + 2 < nk) { GL_LOAD(0, kt + 2) }
;     MMA_TILE(0)
;     LDS_STORE(1, 1)
;     if (VAR != 4) __syncthreads();
;     if (kt + 3 < nk) { GL_LOAD(1, kt + 3) }
;     MMA_TILE(1)
;     if (kt + 2 < nk) { LDS_STORE(0, 0) }
;     if (VAR != 4) __syncthreads();
	v_mfma_f32_16x16x32_f16 v[138:141], v[202:205], v[198:201], v[138:141]
	v_mfma_f32_16x16x32_f16 v[92:95], v[202:205], v[206:209], v[92:95]
	v_mfma_f32_16x16x32_f16 v[142:145], v[210:213], v[198:201], v[142:145]
	v_mfma_f32_16x16x32_f16 v[158:161], v[210:213], v[206:209], v[158:161]
	v_mfma_f32_16x16x32_f16 v[166:169], v[202:205], v[220:223], v[166:169]
	v_mfma_f32_16x16x32_f16 v[68:71], v[202:205], v[228:231], v[68:71]
	ds_read_b128 v[202:205], v136 offset:49152
	v_mfma_f32_16x16x32_f16 v[190:193], v[210:213], v[220:223], v[190:193]
	v_mfma_f32_16x16x32_f16 v[76:79], v[210:213], v[228:231], v[76:79]
	ds_read_b128 v[210:213], v136 offset:51200
	v_mfma_f32_16x16x32_f16 v[154:157], v[224:227], v[198:201], v[154:157]
	v_mfma_f32_16x16x32_f16 v[162:165], v[224:227], v[206:209], v[162:165]
	v_mfma_f32_16x16x32_f16 v[64:67], v[232:235], v[198:201], v[64:67]
	ds_read_b128 v[198:201], v133 offset:16384
	v_mfma_f32_16x16x32_f16 v[72:75], v[232:235], v[206:209], v[72:75]
	ds_read_b128 v[206:209], v133 offset:18432
	v_mfma_f32_16x16x32_f16 v[194:197], v[224:227], v[220:223], v[194:197]
	v_and_b32_e32 v30, 7, v148
	v_bfe_u32 v31, v148, 4, 3
	v_xor_b32_e32 v31, v31, v30
	v_sub_u32_e32 v31, v31, v30
	v_lshlrev_b32_e32 v30, 4, v31
	v_add_u32_e32 v30, 0x200, v30
	v_ashrrev_i32_e32 v31, 31, v30
	v_mfma_f32_16x16x32_f16 v[84:87], v[224:227], v[228:231], v[84:87]
	ds_read_b128 v[224:227], v136 offset:53248
	v_mfma_f32_16x16x32_f16 v[80:83], v[232:235], v[220:223], v[80:83]
	ds_read_b128 v[220:223], v133 offset:20480
	v_mfma_f32_16x16x32_f16 v[88:91], v[232:235], v[228:231], v[88:91]
	ds_read_b128 v[228:231], v133 offset:22528
	s_waitcnt lgkmcnt(4)
	v_mfma_f32_16x16x32_f16 v[138:141], v[202:205], v[198:201], v[138:141]
	ds_read_b128 v[232:235], v136 offset:55296
	s_waitcnt lgkmcnt(4)
	v_mfma_f32_16x16x32_f16 v[92:95], v[202:205], v[206:209], v[92:95]
	v_lshl_add_u64 v[0:1], v[108:109], 0, v[30:31]
	s_mov_b32 m0, s60
	s_nop 0
	global_load_lds_dwordx4 v[0:1], off
	v_mfma_f32_16x16x32_f16 v[142:145], v[210:213], v[198:201], v[142:145]
	v_lshl_add_u64 v[4:5], v[110:111], 0, v[30:31]
	s_mov_b32 m0, s68
	s_nop 0
	global_load_lds_dwordx4 v[4:5], off
	v_mfma_f32_16x16x32_f16 v[158:161], v[210:213], v[206:209], v[158:161]
	v_lshl_add_u64 v[8:9], v[112:113], 0, v[30:31]
	s_mov_b32 m0, s72
	s_nop 0
	global_load_lds_dwordx4 v[8:9], off
	s_waitcnt lgkmcnt(2)
	v_mfma_f32_16x16x32_f16 v[166:169], v[202:205], v[220:223], v[166:169]
	v_lshl_add_u64 v[12:13], v[114:115], 0, v[30:31]
	s_mov_b32 m0, s64
	s_nop 0
	global_load_lds_dwordx4 v[12:13], off
	s_waitcnt lgkmcnt(1)
	v_mfma_f32_16x16x32_f16 v[68:71], v[202:205], v[228:231], v[68:71]
	ds_read_b128 v[202:205], v135 offset:49152
	v_mfma_f32_16x16x32_f16 v[190:193], v[210:213], v[220:223], v[190:193]
	v_lshl_add_u64 v[16:17], v[116:117], 0, v[30:31]
	s_mov_b32 m0, s62
	s_nop 0
	global_load_lds_dwordx4 v[16:17], off
	v_mfma_f32_16x16x32_f16 v[76:79], v[210:213], v[228:231], v[76:79]
	ds_read_b128 v[210:213], v135 offset:51200
	v_mfma_f32_16x16x32_f16 v[154:157], v[224:227], v[198:201], v[154:157]
	v_lshl_add_u64 v[20:21], v[118:119], 0, v[30:31]
	s_mov_b32 m0, s70
	s_nop 0
	global_load_lds_dwordx4 v[20:21], off
	v_mfma_f32_16x16x32_f16 v[162:165], v[224:227], v[206:209], v[162:165]
	v_lshl_add_u64 v[24:25], v[120:121], 0, v[30:31]
	s_mov_b32 m0, s74
	s_nop 0
	global_load_lds_dwordx4 v[24:25], off
	s_waitcnt lgkmcnt(2)
	v_mfma_f32_16x16x32_f16 v[64:67], v[232:235], v[198:201], v[64:67]
	ds_read_b128 v[198:201], v134 offset:16384
	v_mfma_f32_16x16x32_f16 v[72:75], v[232:235], v[206:209], v[72:75]
	ds_read_b128 v[206:209], v134 offset:18432
	v_mfma_f32_16x16x32_f16 v[194:197], v[224:227], v[220:223], v[194:197]
	v_lshl_add_u64 v[28:29], v[122:123], 0, v[30:31]
	s_mov_b32 m0, s66
	s_nop 0
	global_load_lds_dwordx4 v[28:29], off
	v_mfma_f32_16x16x32_f16 v[84:87], v[224:227], v[228:231], v[84:87]
	ds_read_b128 v[224:227], v135 offset:53248
	v_mfma_f32_16x16x32_f16 v[80:83], v[232:235], v[220:223], v[80:83]
	ds_read_b128 v[220:223], v134 offset:20480
	v_mfma_f32_16x16x32_f16 v[88:91], v[232:235], v[228:231], v[88:91]
	ds_read_b128 v[228:231], v134 offset:22528
	ds_read_b128 v[232:235], v135 offset:55296
	s_waitcnt vmcnt(0) lgkmcnt(0)
	s_barrier
	v_mfma_f32_16x16x32_f16 v[138:141], v[202:205], v[198:201], v[138:141]
	v_mfma_f32_16x16x32_f16 v[92:95], v[202:205], v[206:209], v[92:95]
	v_mfma_f32_16x16x32_f16 v[142:145], v[210:213], v[198:201], v[142:145]
	v_mfma_f32_16x16x32_f16 v[158:161], v[210:213], v[206:209], v[158:161]
	v_mfma_f32_16x16x32_f16 v[166:169], v[202:205], v[220:223], v[166:169]
	v_mfma_f32_16x16x32_f16 v[68:71], v[202:205], v[228:231], v[68:71]
	ds_read_b128 v[202:205], v136 offset:32768
	v_mfma_f32_16x16x32_f16 v[190:193], v[210:213], v[220:223], v[190:193]
	v_mfma_f32_16x16x32_f16 v[76:79], v[210:213], v[228:231], v[76:79]
	ds_read_b128 v[210:213], v136 offset:34816
	v_mfma_f32_16x16x32_f16 v[154:157], v[224:227], v[198:201], v[154:157]
	v_mfma_f32_16x16x32_f16 v[162:165], v[224:227], v[206:209], v[162:165]
	v_mfma_f32_16x16x32_f16 v[64:67], v[232:235], v[198:201], v[64:67]
	ds_read_b128 v[198:201], v133
	v_mfma_f32_16x16x32_f16 v[72:75], v[232:235], v[206:209], v[72:75]
	ds_read_b128 v[206:209], v133 offset:2048
	v_mfma_f32_16x16x32_f16 v[194:197], v[224:227], v[220:223], v[194:197]
	v_and_b32_e32 v62, 7, v148
	v_bfe_u32 v63, v148, 4, 3
	v_xor_b32_e32 v63, v63, v62
	v_sub_u32_e32 v63, v63, v62
	v_lshlrev_b32_e32 v62, 4, v63
	v_add_u32_e32 v62, 0x280, v62
	v_ashrrev_i32_e32 v63, 31, v62
	v_mfma_f32_16x16x32_f16 v[84:87], v[224:227], v[228:231], v[84:87]
	ds_read_b128 v[224:227], v136 offset:36864
	v_mfma_f32_16x16x32_f16 v[80:83], v[232:235], v[220:223], v[80:83]
	ds_read_b128 v[220:223], v133 offset:4096
	v_mfma_f32_16x16x32_f16 v[88:91], v[232:235], v[228:231], v[88:91]
	ds_read_b128 v[228:231], v133 offset:6144
	s_waitcnt lgkmcnt(4)
; #define GL_LOAD(s_, kt_) if (VAR != 1) { a##s_##0 = GL_A(0, kt_); a##s_##1 = GL_A(1, kt_); a##s_##2 = GL_A(2, kt_); a##s_##3 = GL_A(3, kt_); b##s_##0 = GL_B(0, kt_); b##s_##1 = GL_B(1, kt_); b##s_##2 = GL_B(2, kt_); b##s_##3 = GL_B(3, kt_); }
; #define LDS_STORE(s_, buf_) if (VAR != 2) { LDS_ST1(sA, 0, buf_, a##s_##0) LDS_ST1(sA, 1, buf_, a##s_##1) LDS_ST1(sA, 2, buf_, a##s_##2) LDS_ST1(sA, 3, buf_, a##s_##3) LDS_ST1(sB, 0, buf_, b##s_##0) LDS_ST1(sB, 1, buf_, b##s_##1) LDS_ST1(sB, 2, buf_, b##s_##2) LDS_ST1(sB, 3, buf_, b##s_##3) }
;     ...
;   GL_LOAD(0, 0)
;   GL_LOAD(1, 1)
;   LDS_STORE(0, 0)
;   if (VAR != 4) __syncthreads();
; #pragma unroll
;   for (int kt = 0; kt < nk; kt += 2) {
;     if (kt + 2 < nk) { GL_LOAD(0, kt + 2) }
;     MMA_TILE(0)
;     LDS_STORE(1, 1)
;     if (VAR != 4) __syncthreads();
;     if (kt + 3 < nk) { GL_LOAD(1, kt + 3) }
;     MMA_TILE(1)
;     if (kt + 2 < nk) { LDS_STORE(0, 0) }
;     if (VAR != 4) __syncthreads();
	v_mfma_f32_16x16x32_f16 v[138:141], v[202:205], v[198:201], v[138:141]
	ds_read_b128 v[232:235], v136 offset:38912
	s_waitcnt lgkmcnt(4)
	v_mfma_f32_16x16x32_f16 v[92:95], v[202:205], v[206:209], v[92:95]
	v_lshl_add_u64 v[32:33], v[108:109], 0, v[62:63]
	s_mov_b32 m0, s61
	s_nop 0
	global_load_lds_dwordx4 v[32:33], off
	v_mfma_f32_16x16x32_f16 v[142:145], v[210:213], v[198:201], v[142:145]
	v_lshl_add_u64 v[36:37], v[110:111], 0, v[62:63]
	s_mov_b32 m0, s69
	s_nop 0
	global_load_lds_dwordx4 v[36:37], off
	v_mfma_f32_16x16x32_f16 v[158:161], v[210:213], v[206:209], v[158:161]
	v_lshl_add_u64 v[40:41], v[112:113], 0, v[62:63]
	s_mov_b32 m0, s73
	s_nop 0
	global_load_lds_dwordx4 v[40:41], off
	s_waitcnt lgkmcnt(2)
	v_mfma_f32_16x16x32_f16 v[166:169], v[202:205], v[220:223], v[166:169]
	v_lshl_add_u64 v[44:45], v[114:115], 0, v[62:63]
	s_mov_b32 m0, s65
	s_nop 0
	global_load_lds_dwordx4 v[44:45], off
	s_waitcnt lgkmcnt(1)
	v_mfma_f32_16x16x32_f16 v[68:71], v[202:205], v[228:231], v[68:71]
	ds_read_b128 v[202:205], v135 offset:32768
	v_mfma_f32_16x16x32_f16 v[190:193], v[210:213], v[220:223], v[190:193]
	v_lshl_add_u64 v[48:49], v[116:117], 0, v[62:63]
	s_mov_b32 m0, s63
	s_nop 0
	global_load_lds_dwordx4 v[48:49], off
	v_mfma_f32_16x16x32_f16 v[76:79], v[210:213], v[228:231], v[76:79]
	ds_read_b128 v[210:213], v135 offset:34816
	v_mfma_f32_16x16x32_f16 v[154:157], v[224:227], v[198:201], v[154:157]
	v_lshl_add_u64 v[52:53], v[118:119], 0, v[62:63]
	s_mov_b32 m0, s71
	s_nop 0
	global_load_lds_dwordx4 v[52:53], off
	v_mfma_f32_16x16x32_f16 v[162:165], v[224:227], v[206:209], v[162:165]
	v_lshl_add_u64 v[56:57], v[120:121], 0, v[62:63]
	s_mov_b32 m0, s75
	s_nop 0
	global_load_lds_dwordx4 v[56:57], off
	s_waitcnt lgkmcnt(2)
	v_mfma_f32_16x16x32_f16 v[64:67], v[232:235], v[198:201], v[64:67]
	ds_read_b128 v[198:201], v134
	v_mfma_f32_16x16x32_f16 v[72:75], v[232:235], v[206:209], v[72:75]
	ds_read_b128 v[206:209], v134 offset:2048
	v_mfma_f32_16x16x32_f16 v[194:197], v[224:227], v[220:223], v[194:197]
	v_lshl_add_u64 v[60:61], v[122:123], 0, v[62:63]
	s_mov_b32 m0, s67
	s_nop 0
	global_load_lds_dwordx4 v[60:61], off
	v_mfma_f32_16x16x32_f16 v[84:87], v[224:227], v[228:231], v[84:87]
	ds_read_b128 v[224:227], v135 offset:36864
	v_mfma_f32_16x16x32_f16 v[80:83], v[232:235], v[220:223], v[80:83]
	ds_read_b128 v[220:223], v134 offset:4096
	v_mfma_f32_16x16x32_f16 v[88:91], v[232:235], v[228:231], v[88:91]
	ds_read_b128 v[228:231], v134 offset:6144
	ds_read_b128 v[232:235], v135 offset:38912
	s_waitcnt vmcnt(0) lgkmcnt(0)
	s_barrier
	v_mfma_f32_16x16x32_f16 v[138:141], v[202:205], v[198:201], v[138:141]
	v_mfma_f32_16x16x32_f16 v[92:95], v[202:205], v[206:209], v[92:95]
	v_mfma_f32_16x16x32_f16 v[142:145], v[210:213], v[198:201], v[142:145]
	v_mfma_f32_16x16x32_f16 v[158:161], v[210:213], v[206:209], v[158:161]
	v_mfma_f32_16x16x32_f16 v[166:169], v[202:205], v[220:223], v[166:169]
	v_mfma_f32_16x16x32_f16 v[68:71], v[202:205], v[228:231], v[68:71]
	ds_read_b128 v[202:205], v136 offset:49152
	v_mfma_f32_16x16x32_f16 v[190:193], v[210:213], v[220:223], v[190:193]
	v_mfma_f32_16x16x32_f16 v[76:79], v[210:213], v[228:231], v[76:79]
	ds_read_b128 v[210:213], v136 offset:51200
	v_mfma_f32_16x16x32_f16 v[154:157], v[224:227], v[198:201], v[154:157]
	v_mfma_f32_16x16x32_f16 v[162:165], v[224:227], v[206:209], v[162:165]
	v_mfma_f32_16x16x32_f16 v[64:67], v[232:235], v[198:201], v[64:67]
	ds_read_b128 v[198:201], v133 offset:16384
	v_mfma_f32_16x16x32_f16 v[72:75], v[232:235], v[206:209], v[72:75]
	ds_read_b128 v[206:209], v133 offset:18432
	v_mfma_f32_16x16x32_f16 v[194:197], v[224:227], v[220:223], v[194:197]
	v_and_b32_e32 v30, 7, v148
	v_bfe_u32 v31, v148, 4, 3
	v_xor_b32_e32 v31, v31, v30
	v_sub_u32_e32 v31, v31, v30
	v_lshlrev_b32_e32 v30, 4, v31
	v_add_u32_e32 v30, 0x300, v30
	v_ashrrev_i32_e32 v31, 31, v30
	v_mfma_f32_16x16x32_f16 v[84:87], v[224:227], v[228:231], v[84:87]
	ds_read_b128 v[224:227], v136 offset:53248
	v_mfma_f32_16x16x32_f16 v[80:83], v[232:235], v[220:223], v[80:83]
	ds_read_b128 v[220:223], v133 offset:20480
	v_mfma_f32_16x16x32_f16 v[88:91], v[232:235], v[228:231], v[88:91]
	ds_read_b128 v[228:231], v133 offset:22528
	s_waitcnt lgkmcnt(4)
	v_mfma_f32_16x16x32_f16 v[138:141], v[202:205], v[198:201], v[138:141]
	ds_read_b128 v[232:235], v136 offset:55296
	s_waitcnt lgkmcnt(4)
	v_mfma_f32_16x16x32_f16 v[92:95], v[202:205], v[206:209], v[92:95]
	v_lshl_add_u64 v[0:1], v[108:109], 0, v[30:31]
	s_mov_b32 m0, s60
	s_nop 0
	global_load_lds_dwordx4 v[0:1], off
	v_mfma_f32_16x16x32_f16 v[142:145], v[210:213], v[198:201], v[142:145]
	v_lshl_add_u64 v[4:5], v[110:111], 0, v[30:31]
	s_mov_b32 m0, s68
	s_nop 0
	global_load_lds_dwordx4 v[4:5], off
	v_mfma_f32_16x16x32_f16 v[158:161], v[210:213], v[206:209], v[158:161]
	v_lshl_add_u64 v[8:9], v[112:113], 0, v[30:31]
	s_mov_b32 m0, s72
	s_nop 0
	global_load_lds_dwordx4 v[8:9], off
	s_waitcnt lgkmcnt(2)
	v_mfma_f32_16x16x32_f16 v[166:169], v[202:205], v[220:223], v[166:169]
	v_lshl_add_u64 v[12:13], v[114:115], 0, v[30:31]
	s_mov_b32 m0, s64
	s_nop 0
	global_load_lds_dwordx4 v[12:13], off
	s_waitcnt lgkmcnt(1)
	v_mfma_f32_16x16x32_f16 v[68:71], v[202:205], v[228:231], v[68:71]
	ds_read_b128 v[202:205], v135 offset:49152
	v_mfma_f32_16x16x32_f16 v[190:193], v[210:213], v[220:223], v[190:193]
	v_lshl_add_u64 v[16:17], v[116:117], 0, v[30:31]
	s_mov_b32 m0, s62
	s_nop 0
	global_load_lds_dwordx4 v[16:17], off
	v_mfma_f32_16x16x32_f16 v[76:79], v[210:213], v[228:231], v[76:79]
	ds_read_b128 v[210:213], v135 offset:51200
	v_mfma_f32_16x16x32_f16 v[154:157], v[224:227], v[198:201], v[154:157]
	v_lshl_add_u64 v[20:21], v[118:119], 0, v[30:31]
	s_mov_b32 m0, s70
	s_nop 0
	global_load_lds_dwordx4 v[20:21], off
	v_mfma_f32_16x16x32_f16 v[162:165], v[224:227], v[206:209], v[162:165]
	v_lshl_add_u64 v[24:25], v[120:121], 0, v[30:31]
	s_mov_b32 m0, s74
	s_nop 0
	global_load_lds_dwordx4 v[24:25], off
	s_waitcnt lgkmcnt(2)
	v_mfma_f32_16x16x32_f16 v[64:67], v[232:235], v[198:201], v[64:67]
	ds_read_b128 v[198:201], v134 offset:16384
	v_mfma_f32_16x16x32_f16 v[72:75], v[232:235], v[206:209], v[72:75]
	ds_read_b128 v[206:209], v134 offset:18432
	v_mfma_f32_16x16x32_f16 v[194:197], v[224:227], v[220:223], v[194:197]
	v_lshl_add_u64 v[28:29], v[122:123], 0, v[30:31]
	s_mov_b32 m0, s66
	s_nop 0
	global_load_lds_dwordx4 v[28:29], off
	v_mfma_f32_16x16x32_f16 v[84:87], v[224:227], v[228:231], v[84:87]
	ds_read_b128 v[224:227], v135 offset:53248
	v_mfma_f32_16x16x32_f16 v[80:83], v[232:235], v[220:223], v[80:83]
	ds_read_b128 v[220:223], v134 offset:20480
	v_mfma_f32_16x16x32_f16 v[88:91], v[232:235], v[228:231], v[88:91]
	ds_read_b128 v[228:231], v134 offset:22528
	ds_read_b128 v[232:235], v135 offset:55296
	s_waitcnt vmcnt(0) lgkmcnt(0)
	s_barrier
; #define GL_LOAD(s_, kt_) if (VAR != 1) { a##s_##0 = GL_A(0, kt_); a##s_##1 = GL_A(1, kt_); a##s_##2 = GL_A(2, kt_); a##s_##3 = GL_A(3, kt_); b##s_##0 = GL_B(0, kt_); b##s_##1 = GL_B(1, kt_); b##s_##2 = GL_B(2, kt_); b##s_##3 = GL_B(3, kt_); }
; #define LDS_STORE(s_, buf_) if (VAR != 2) { LDS_ST1(sA, 0, buf_, a##s_##0) LDS_ST1(sA, 1, buf_, a##s_##1) LDS_ST1(sA, 2, buf_, a##s_##2) LDS_ST1(sA, 3, buf_, a##s_##3) LDS_ST1(sB, 0, buf_, b##s_##0) LDS_ST1(sB, 1, buf_, b##s_##1) LDS_ST1(sB, 2, buf_, b##s_##2) LDS_ST1(sB, 3, buf_, b##s_##3) }
;     ...
;   GL_LOAD(0, 0)
;   GL_LOAD(1, 1)
;   LDS_STORE(0, 0)
;   if (VAR != 4) __syncthreads();
; #pragma unroll
;   for (int kt = 0; kt < nk; kt += 2) {
;     if (kt + 2 < nk) { GL_LOAD(0, kt + 2) }
;     MMA_TILE(0)
;     LDS_STORE(1, 1)
;     if (VAR != 4) __syncthreads();
;     if (kt + 3 < nk) { GL_LOAD(1, kt + 3) }
;     MMA_TILE(1)
;     if (kt + 2 < nk) { LDS_STORE(0, 0) }
;     if (VAR != 4) __syncthreads();
	v_mfma_f32_16x16x32_f16 v[138:141], v[202:205], v[198:201], v[138:141]
	v_mfma_f32_16x16x32_f16 v[92:95], v[202:205], v[206:209], v[92:95]
	v_mfma_f32_16x16x32_f16 v[142:145], v[210:213], v[198:201], v[142:145]
	v_mfma_f32_16x16x32_f16 v[158:161], v[210:213], v[206:209], v[158:161]
	v_mfma_f32_16x16x32_f16 v[166:169], v[202:205], v[220:223], v[166:169]
	v_mfma_f32_16x16x32_f16 v[68:71], v[202:205], v[228:231], v[68:71]
	ds_read_b128 v[202:205], v136 offset:32768
	v_mfma_f32_16x16x32_f16 v[190:193], v[210:213], v[220:223], v[190:193]
	v_mfma_f32_16x16x32_f16 v[76:79], v[210:213], v[228:231], v[76:79]
	ds_read_b128 v[210:213], v136 offset:34816
	v_mfma_f32_16x16x32_f16 v[154:157], v[224:227], v[198:201], v[154:157]
	v_mfma_f32_16x16x32_f16 v[162:165], v[224:227], v[206:209], v[162:165]
	v_mfma_f32_16x16x32_f16 v[64:67], v[232:235], v[198:201], v[64:67]
	ds_read_b128 v[198:201], v133
	v_mfma_f32_16x16x32_f16 v[72:75], v[232:235], v[206:209], v[72:75]
	ds_read_b128 v[206:209], v133 offset:2048
	v_mfma_f32_16x16x32_f16 v[194:197], v[224:227], v[220:223], v[194:197]
	v_and_b32_e32 v62, 7, v148
	v_bfe_u32 v63, v148, 4, 3
	v_xor_b32_e32 v63, v63, v62
	v_sub_u32_e32 v63, v63, v62
	v_lshlrev_b32_e32 v62, 4, v63
	v_add_u32_e32 v62, 0x380, v62
	v_ashrrev_i32_e32 v63, 31, v62
	v_mfma_f32_16x16x32_f16 v[84:87], v[224:227], v[228:231], v[84:87]
	ds_read_b128 v[224:227], v136 offset:36864
	v_mfma_f32_16x16x32_f16 v[80:83], v[232:235], v[220:223], v[80:83]
	ds_read_b128 v[220:223], v133 offset:4096
	v_mfma_f32_16x16x32_f16 v[88:91], v[232:235], v[228:231], v[88:91]
	ds_read_b128 v[228:231], v133 offset:6144
	s_waitcnt lgkmcnt(4)
	v_mfma_f32_16x16x32_f16 v[138:141], v[202:205], v[198:201], v[138:141]
	ds_read_b128 v[232:235], v136 offset:38912
	s_waitcnt lgkmcnt(4)
	v_mfma_f32_16x16x32_f16 v[92:95], v[202:205], v[206:209], v[92:95]
	v_lshl_add_u64 v[32:33], v[108:109], 0, v[62:63]
	s_mov_b32 m0, s61
	s_nop 0
	global_load_lds_dwordx4 v[32:33], off
	v_mfma_f32_16x16x32_f16 v[142:145], v[210:213], v[198:201], v[142:145]
	v_lshl_add_u64 v[36:37], v[110:111], 0, v[62:63]
	s_mov_b32 m0, s69
	s_nop 0
	global_load_lds_dwordx4 v[36:37], off
	v_mfma_f32_16x16x32_f16 v[158:161], v[210:213], v[206:209], v[158:161]
	v_lshl_add_u64 v[40:41], v[112:113], 0, v[62:63]
	s_mov_b32 m0, s73
	s_nop 0
	global_load_lds_dwordx4 v[40:41], off
	s_waitcnt lgkmcnt(2)
	v_mfma_f32_16x16x32_f16 v[166:169], v[202:205], v[220:223], v[166:169]
	v_lshl_add_u64 v[44:45], v[114:115], 0, v[62:63]
	s_mov_b32 m0, s65
	s_nop 0
	global_load_lds_dwordx4 v[44:45], off
	s_waitcnt lgkmcnt(1)
	v_mfma_f32_16x16x32_f16 v[68:71], v[202:205], v[228:231], v[68:71]
	ds_read_b128 v[202:205], v135 offset:32768
	v_mfma_f32_16x16x32_f16 v[190:193], v[210:213], v[220:223], v[190:193]
	v_lshl_add_u64 v[48:49], v[116:117], 0, v[62:63]
	s_mov_b32 m0, s63
	s_nop 0
	global_load_lds_dwordx4 v[48:49], off
	v_mfma_f32_16x16x32_f16 v[76:79], v[210:213], v[228:231], v[76:79]
	ds_read_b128 v[210:213], v135 offset:34816
	v_mfma_f32_16x16x32_f16 v[154:157], v[224:227], v[198:201], v[154:157]
	v_lshl_add_u64 v[52:53], v[118:119], 0, v[62:63]
	s_mov_b32 m0, s71
	s_nop 0
	global_load_lds_dwordx4 v[52:53], off
	v_mfma_f32_16x16x32_f16 v[162:165], v[224:227], v[206:209], v[162:165]
	v_lshl_add_u64 v[56:57], v[120:121], 0, v[62:63]
	s_mov_b32 m0, s75
	s_nop 0
	global_load_lds_dwordx4 v[56:57], off
	s_waitcnt lgkmcnt(2)
	v_mfma_f32_16x16x32_f16 v[64:67], v[232:235], v[198:201], v[64:67]
	ds_read_b128 v[198:201], v134
	v_mfma_f32_16x16x32_f16 v[72:75], v[232:235], v[206:209], v[72:75]
	ds_read_b128 v[206:209], v134 offset:2048
	v_mfma_f32_16x16x32_f16 v[194:197], v[224:227], v[220:223], v[194:197]
	v_lshl_add_u64 v[60:61], v[122:123], 0, v[62:63]
	s_mov_b32 m0, s67
	s_nop 0
	global_load_lds_dwordx4 v[60:61], off
	v_mfma_f32_16x16x32_f16 v[84:87], v[224:227], v[228:231], v[84:87]
	ds_read_b128 v[224:227], v135 offset:36864
	v_mfma_f32_16x16x32_f16 v[80:83], v[232:235], v[220:223], v[80:83]
	ds_read_b128 v[220:223], v134 offset:4096
	v_mfma_f32_16x16x32_f16 v[88:91], v[232:235], v[228:231], v[88:91]
	ds_read_b128 v[228:231], v134 offset:6144
	ds_read_b128 v[232:235], v135 offset:38912
	s_waitcnt vmcnt(0) lgkmcnt(0)
	s_barrier
	v_mfma_f32_16x16x32_f16 v[138:141], v[202:205], v[198:201], v[138:141]
	v_mfma_f32_16x16x32_f16 v[92:95], v[202:205], v[206:209], v[92:95]
	v_mfma_f32_16x16x32_f16 v[142:145], v[210:213], v[198:201], v[142:145]
	v_mfma_f32_16x16x32_f16 v[158:161], v[210:213], v[206:209], v[158:161]
	v_mfma_f32_16x16x32_f16 v[166:169], v[202:205], v[220:223], v[166:169]
	v_mfma_f32_16x16x32_f16 v[68:71], v[202:205], v[228:231], v[68:71]
	ds_read_b128 v[202:205], v136 offset:49152
	v_mfma_f32_16x16x32_f16 v[190:193], v[210:213], v[220:223], v[190:193]
	v_mfma_f32_16x16x32_f16 v[76:79], v[210:213], v[228:231], v[76:79]
	ds_read_b128 v[210:213], v136 offset:51200
	v_mfma_f32_16x16x32_f16 v[154:157], v[224:227], v[198:201], v[154:157]
	v_mfma_f32_16x16x32_f16 v[162:165], v[224:227], v[206:209], v[162:165]
	v_mfma_f32_16x16x32_f16 v[64:67], v[232:235], v[198:201], v[64:67]
	ds_read_b128 v[198:201], v133 offset:16384
	v_mfma_f32_16x16x32_f16 v[72:75], v[232:235], v[206:209], v[72:75]
	ds_read_b128 v[206:209], v133 offset:18432
	v_mfma_f32_16x16x32_f16 v[194:197], v[224:227], v[220:223], v[194:197]
	v_and_b32_e32 v30, 7, v148
	v_bfe_u32 v31, v148, 4, 3
	v_xor_b32_e32 v31, v31, v30
	v_sub_u32_e32 v31, v31, v30
	v_lshlrev_b32_e32 v30, 4, v31
	v_add_u32_e32 v30, 0x400, v30
	v_ashrrev_i32_e32 v31, 31, v30
	v_mfma_f32_16x16x32_f16 v[84:87], v[224:227], v[228:231], v[84:87]
	ds_read_b128 v[224:227], v136 offset:53248
	v_mfma_f32_16x16x32_f16 v[80:83], v[232:235], v[220:223], v[80:83]
	ds_read_b128 v[220:223], v133 offset:20480
	v_mfma_f32_16x16x32_f16 v[88:91], v[232:235], v[228:231], v[88:91]
	ds_read_b128 v[228:231], v133 offset:22528
	s_waitcnt lgkmcnt(4)
; #define GL_LOAD(s_, kt_) if (VAR != 1) { a##s_##0 = GL_A(0, kt_); a##s_##1 = GL_A(1, kt_); a##s_##2 = GL_A(2, kt_); a##s_##3 = GL_A(3, kt_); b##s_##0 = GL_B(0, kt_); b##s_##1 = GL_B(1, kt_); b##s_##2 = GL_B(2, kt_); b##s_##3 = GL_B(3, kt_); }
; #define LDS_STORE(s_, buf_) if (VAR != 2) { LDS_ST1(sA, 0, buf_, a##s_##0) LDS_ST1(sA, 1, buf_, a##s_##1) LDS_ST1(sA, 2, buf_, a##s_##2) LDS_ST1(sA, 3, buf_, a##s_##3) LDS_ST1(sB, 0, buf_, b##s_##0) LDS_ST1(sB, 1, buf_, b##s_##1) LDS_ST1(sB, 2, buf_, b##s_##2) LDS_ST1(sB, 3, buf_, b##s_##3) }
;     ...
;   GL_LOAD(0, 0)
;   GL_LOAD(1, 1)
;   LDS_STORE(0, 0)
;   if (VAR != 4) __syncthreads();
; #pragma unroll
;   for (int kt = 0; kt < nk; kt += 2) {
;     if (kt + 2 < nk) { GL_LOAD(0, kt + 2) }
;     MMA_TILE(0)
;     LDS_STORE(1, 1)
;     if (VAR != 4) __syncthreads();
;     if (kt + 3 < nk) { GL_LOAD(1, kt + 3) }
;     MMA_TILE(1)
;     if (kt + 2 < nk) { LDS_STORE(0, 0) }
;     if (VAR != 4) __syncthreads();
	v_mfma_f32_16x16x32_f16 v[138:141], v[202:205], v[198:201], v[138:141]
	ds_read_b128 v[232:235], v136 offset:55296
	s_waitcnt lgkmcnt(4)
	v_mfma_f32_16x16x32_f16 v[92:95], v[202:205], v[206:209], v[92:95]
	v_lshl_add_u64 v[0:1], v[108:109], 0, v[30:31]
	s_mov_b32 m0, s60
	s_nop 0
	global_load_lds_dwordx4 v[0:1], off
	v_mfma_f32_16x16x32_f16 v[142:145], v[210:213], v[198:201], v[142:145]
	v_lshl_add_u64 v[4:5], v[110:111], 0, v[30:31]
	s_mov_b32 m0, s68
	s_nop 0
	global_load_lds_dwordx4 v[4:5], off
	v_mfma_f32_16x16x32_f16 v[158:161], v[210:213], v[206:209], v[158:161]
	v_lshl_add_u64 v[8:9], v[112:113], 0, v[30:31]
	s_mov_b32 m0, s72
	s_nop 0
	global_load_lds_dwordx4 v[8:9], off
	s_waitcnt lgkmcnt(2)
	v_mfma_f32_16x16x32_f16 v[166:169], v[202:205], v[220:223], v[166:169]
	v_lshl_add_u64 v[12:13], v[114:115], 0, v[30:31]
	s_mov_b32 m0, s64
	s_nop 0
	global_load_lds_dwordx4 v[12:13], off
	s_waitcnt lgkmcnt(1)
	v_mfma_f32_16x16x32_f16 v[68:71], v[202:205], v[228:231], v[68:71]
	ds_read_b128 v[202:205], v135 offset:49152
	v_mfma_f32_16x16x32_f16 v[190:193], v[210:213], v[220:223], v[190:193]
	v_lshl_add_u64 v[16:17], v[116:117], 0, v[30:31]
	s_mov_b32 m0, s62
	s_nop 0
	global_load_lds_dwordx4 v[16:17], off
	v_mfma_f32_16x16x32_f16 v[76:79], v[210:213], v[228:231], v[76:79]
	ds_read_b128 v[210:213], v135 offset:51200
	v_mfma_f32_16x16x32_f16 v[154:157], v[224:227], v[198:201], v[154:157]
	v_lshl_add_u64 v[20:21], v[118:119], 0, v[30:31]
	s_mov_b32 m0, s70
	s_nop 0
	global_load_lds_dwordx4 v[20:21], off
	v_mfma_f32_16x16x32_f16 v[162:165], v[224:227], v[206:209], v[162:165]
	v_lshl_add_u64 v[24:25], v[120:121], 0, v[30:31]
	s_mov_b32 m0, s74
	s_nop 0
	global_load_lds_dwordx4 v[24:25], off
	s_waitcnt lgkmcnt(2)
	v_mfma_f32_16x16x32_f16 v[64:67], v[232:235], v[198:201], v[64:67]
	ds_read_b128 v[198:201], v134 offset:16384
	v_mfma_f32_16x16x32_f16 v[72:75], v[232:235], v[206:209], v[72:75]
	ds_read_b128 v[206:209], v134 offset:18432
	v_mfma_f32_16x16x32_f16 v[194:197], v[224:227], v[220:223], v[194:197]
	v_lshl_add_u64 v[28:29], v[122:123], 0, v[30:31]
	s_mov_b32 m0, s66
	s_nop 0
	global_load_lds_dwordx4 v[28:29], off
	v_mfma_f32_16x16x32_f16 v[84:87], v[224:227], v[228:231], v[84:87]
	ds_read_b128 v[224:227], v135 offset:53248
	v_mfma_f32_16x16x32_f16 v[80:83], v[232:235], v[220:223], v[80:83]
	ds_read_b128 v[220:223], v134 offset:20480
	v_mfma_f32_16x16x32_f16 v[88:91], v[232:235], v[228:231], v[88:91]
	ds_read_b128 v[228:231], v134 offset:22528
	s_waitcnt lgkmcnt(4)
	v_mfma_f32_16x16x32_f16 v[138:141], v[202:205], v[198:201], v[138:141]
	ds_read_b128 v[232:235], v135 offset:55296
	s_waitcnt vmcnt(0) lgkmcnt(0)
	s_barrier
	v_mfma_f32_16x16x32_f16 v[142:145], v[210:213], v[198:201], v[142:145]
	ds_read_b128 v[0:3], v133
	v_mfma_f32_16x16x32_f16 v[158:161], v[210:213], v[206:209], v[158:161]
	ds_read_b128 v[4:7], v136 offset:32768
	v_mfma_f32_16x16x32_f16 v[154:157], v[224:227], v[198:201], v[154:157]
	ds_read_b128 v[8:11], v133 offset:2048
	v_mfma_f32_16x16x32_f16 v[162:165], v[224:227], v[206:209], v[162:165]
	ds_read_b128 v[12:15], v136 offset:34816
	v_mfma_f32_16x16x32_f16 v[190:193], v[210:213], v[220:223], v[190:193]
	ds_read_b128 v[16:19], v133 offset:4096
	v_mfma_f32_16x16x32_f16 v[210:213], v[210:213], v[228:231], v[76:79]
	ds_read_b128 v[20:23], v136 offset:36864
	v_mfma_f32_16x16x32_f16 v[194:197], v[224:227], v[220:223], v[194:197]
	ds_read_b128 v[24:27], v133 offset:6144
	v_mfma_f32_16x16x32_f16 v[224:227], v[224:227], v[228:231], v[84:87]
	ds_read_b128 v[28:31], v136 offset:38912
	v_mfma_f32_16x16x32_f16 v[198:201], v[232:235], v[198:201], v[64:67]
	s_nop 2
	v_mfma_f32_16x16x32_f16 v[236:239], v[202:205], v[206:209], v[92:95]
	v_mfma_f32_16x16x32_f16 v[206:209], v[232:235], v[206:209], v[72:75]
	v_mfma_f32_16x16x32_f16 v[166:169], v[202:205], v[220:223], v[166:169]
	v_mfma_f32_16x16x32_f16 v[220:223], v[232:235], v[220:223], v[80:83]
	v_mfma_f32_16x16x32_f16 v[202:205], v[202:205], v[228:231], v[68:71]
	v_mfma_f32_16x16x32_f16 v[228:231], v[232:235], v[228:231], v[88:91]
	ds_read_b128 v[232:235], v135 offset:38912
	s_nop 0
	s_waitcnt lgkmcnt(7)
	v_mfma_f32_16x16x32_f16 v[138:141], v[4:7], v[0:3], v[138:141]
	s_waitcnt lgkmcnt(5)
	v_mfma_f32_16x16x32_f16 v[142:145], v[12:15], v[0:3], v[142:145]
	s_waitcnt lgkmcnt(3)
	v_mfma_f32_16x16x32_f16 v[154:157], v[20:23], v[0:3], v[154:157]
	s_waitcnt lgkmcnt(1)
	v_mfma_f32_16x16x32_f16 v[0:3], v[28:31], v[0:3], v[198:201]
	v_mfma_f32_16x16x32_f16 v[198:201], v[4:7], v[8:11], v[236:239]
	v_mfma_f32_16x16x32_f16 v[158:161], v[12:15], v[8:11], v[158:161]
	v_and_b32_e32 v62, 7, v148
	v_bfe_u32 v63, v148, 4, 3
	v_xor_b32_e32 v63, v63, v62
	v_sub_u32_e32 v63, v63, v62
	v_lshlrev_b32_e32 v62, 4, v63
	v_add_u32_e32 v62, 0x480, v62
	v_ashrrev_i32_e32 v63, 31, v62
	v_lshl_add_u64 v[32:33], v[108:109], 0, v[62:63]
	s_mov_b32 m0, s61
	s_nop 0
	global_load_lds_dwordx4 v[32:33], off
	v_mfma_f32_16x16x32_f16 v[166:169], v[4:7], v[16:19], v[166:169]
	v_lshl_add_u64 v[36:37], v[110:111], 0, v[62:63]
	s_mov_b32 m0, s69
	s_nop 0
	global_load_lds_dwordx4 v[36:37], off
	v_lshl_add_u64 v[40:41], v[112:113], 0, v[62:63]
	s_mov_b32 m0, s73
	s_nop 0
	global_load_lds_dwordx4 v[40:41], off
	v_mfma_f32_16x16x32_f16 v[4:7], v[4:7], v[24:27], v[202:205]
	s_nop 2
	ds_read_b128 v[202:205], v135 offset:32768
	v_lshl_add_u64 v[44:45], v[114:115], 0, v[62:63]
	s_mov_b32 m0, s65
	s_nop 0
	global_load_lds_dwordx4 v[44:45], off
	v_mfma_f32_16x16x32_f16 v[190:193], v[12:15], v[16:19], v[190:193]
	v_lshl_add_u64 v[48:49], v[116:117], 0, v[62:63]
	s_mov_b32 m0, s63
	s_nop 0
	global_load_lds_dwordx4 v[48:49], off
	v_mfma_f32_16x16x32_f16 v[12:15], v[12:15], v[24:27], v[210:213]
	s_nop 2
	ds_read_b128 v[210:213], v135 offset:34816
	v_lshl_add_u64 v[52:53], v[118:119], 0, v[62:63]
	s_mov_b32 m0, s71
	s_nop 0
	global_load_lds_dwordx4 v[52:53], off
	v_mfma_f32_16x16x32_f16 v[162:165], v[20:23], v[8:11], v[162:165]
	v_lshl_add_u64 v[56:57], v[120:121], 0, v[62:63]
	s_mov_b32 m0, s75
	s_nop 0
	global_load_lds_dwordx4 v[56:57], off
	v_lshl_add_u64 v[60:61], v[122:123], 0, v[62:63]
	s_mov_b32 m0, s67
	s_nop 0
	global_load_lds_dwordx4 v[60:61], off
	v_mfma_f32_16x16x32_f16 v[8:11], v[28:31], v[8:11], v[206:209]
	s_nop 2
	ds_read_b128 v[206:209], v134 offset:2048
	v_mfma_f32_16x16x32_f16 v[194:197], v[20:23], v[16:19], v[194:197]
	v_mfma_f32_16x16x32_f16 v[20:23], v[20:23], v[24:27], v[224:227]
	s_nop 2
	ds_read_b128 v[224:227], v135 offset:36864
	v_mfma_f32_16x16x32_f16 v[16:19], v[28:31], v[16:19], v[220:223]
	s_nop 2
	ds_read_b128 v[220:223], v134 offset:4096
	v_mfma_f32_16x16x32_f16 v[24:27], v[28:31], v[24:27], v[228:231]
	ds_read_b128 v[28:31], v134
	s_waitcnt lgkmcnt(0)
	v_mfma_f32_16x16x32_f16 v[138:141], v[202:205], v[28:31], v[138:141]
	ds_read_b128 v[228:231], v134 offset:6144
	s_waitcnt vmcnt(0) lgkmcnt(0)
	s_barrier
; #define GL_LOAD(s_, kt_) if (VAR != 1) { a##s_##0 = GL_A(0, kt_); a##s_##1 = GL_A(1, kt_); a##s_##2 = GL_A(2, kt_); a##s_##3 = GL_A(3, kt_); b##s_##0 = GL_B(0, kt_); b##s_##1 = GL_B(1, kt_); b##s_##2 = GL_B(2, kt_); b##s_##3 = GL_B(3, kt_); }
; #define LDS_STORE(s_, buf_) if (VAR != 2) { LDS_ST1(sA, 0, buf_, a##s_##0) LDS_ST1(sA, 1, buf_, a##s_##1) LDS_ST1(sA, 2, buf_, a##s_##2) LDS_ST1(sA, 3, buf_, a##s_##3) LDS_ST1(sB, 0, buf_, b##s_##0) LDS_ST1(sB, 1, buf_, b##s_##1) LDS_ST1(sB, 2, buf_, b##s_##2) LDS_ST1(sB, 3, buf_, b##s_##3) }
;     ...
;   GL_LOAD(0, 0)
;   GL_LOAD(1, 1)
;   LDS_STORE(0, 0)
;   if (VAR != 4) __syncthreads();
; #pragma unroll
;   for (int kt = 0; kt < nk; kt += 2) {
;     if (kt + 2 < nk) { GL_LOAD(0, kt + 2) }
;     MMA_TILE(0)
;     LDS_STORE(1, 1)
;     if (VAR != 4) __syncthreads();
;     if (kt + 3 < nk) { GL_LOAD(1, kt + 3) }
;     MMA_TILE(1)
;     if (kt + 2 < nk) { LDS_STORE(0, 0) }
;     if (VAR != 4) __syncthreads();
	v_mfma_f32_16x16x32_f16 v[142:145], v[210:213], v[28:31], v[142:145]
	ds_read_b128 v[32:35], v133 offset:16384
	v_mfma_f32_16x16x32_f16 v[158:161], v[210:213], v[206:209], v[158:161]
	ds_read_b128 v[36:39], v136 offset:49152
	v_mfma_f32_16x16x32_f16 v[154:157], v[224:227], v[28:31], v[154:157]
	ds_read_b128 v[40:43], v133 offset:18432
	v_mfma_f32_16x16x32_f16 v[162:165], v[224:227], v[206:209], v[162:165]
	ds_read_b128 v[44:47], v136 offset:51200
	v_mfma_f32_16x16x32_f16 v[190:193], v[210:213], v[220:223], v[190:193]
	ds_read_b128 v[48:51], v133 offset:20480
	v_mfma_f32_16x16x32_f16 v[210:213], v[210:213], v[228:231], v[12:15]
	ds_read_b128 v[52:55], v136 offset:53248
	v_mfma_f32_16x16x32_f16 v[194:197], v[224:227], v[220:223], v[194:197]
	ds_read_b128 v[56:59], v133 offset:22528
	v_mfma_f32_16x16x32_f16 v[224:227], v[224:227], v[228:231], v[20:23]
	ds_read_b128 v[60:63], v136 offset:55296
	v_mfma_f32_16x16x32_f16 v[236:239], v[232:235], v[28:31], v[0:3]
	v_mfma_f32_16x16x32_f16 v[198:201], v[202:205], v[206:209], v[198:201]
	v_mfma_f32_16x16x32_f16 v[206:209], v[232:235], v[206:209], v[8:11]
	v_mfma_f32_16x16x32_f16 v[166:169], v[202:205], v[220:223], v[166:169]
	v_mfma_f32_16x16x32_f16 v[220:223], v[232:235], v[220:223], v[16:19]
	v_mfma_f32_16x16x32_f16 v[202:205], v[202:205], v[228:231], v[4:7]
	v_mfma_f32_16x16x32_f16 v[228:231], v[232:235], v[228:231], v[24:27]
	ds_read_b128 v[232:235], v135 offset:55296
	s_nop 1
	s_waitcnt lgkmcnt(7)
	v_mfma_f32_16x16x32_f16 v[138:141], v[36:39], v[32:35], v[138:141]
	s_waitcnt lgkmcnt(6)
	v_mfma_f32_16x16x32_f16 v[198:201], v[36:39], v[40:43], v[198:201]
	s_waitcnt lgkmcnt(5)
	v_mfma_f32_16x16x32_f16 v[142:145], v[44:47], v[32:35], v[142:145]
	v_mfma_f32_16x16x32_f16 v[158:161], v[44:47], v[40:43], v[158:161]
	s_waitcnt lgkmcnt(4)
	v_mfma_f32_16x16x32_f16 v[166:169], v[36:39], v[48:51], v[166:169]
	v_and_b32_e32 v94, 7, v148
	v_bfe_u32 v95, v148, 4, 3
	v_xor_b32_e32 v95, v95, v94
	v_sub_u32_e32 v95, v95, v94
	v_lshlrev_b32_e32 v94, 4, v95
	v_add_u32_e32 v94, 0x500, v94
	v_ashrrev_i32_e32 v95, 31, v94
	s_waitcnt lgkmcnt(2)
	v_mfma_f32_16x16x32_f16 v[36:39], v[36:39], v[56:59], v[202:205]
	s_nop 2
	ds_read_b128 v[202:205], v135 offset:49152
	v_lshl_add_u64 v[64:65], v[108:109], 0, v[94:95]
	s_mov_b32 m0, s60
	s_nop 0
	global_load_lds_dwordx4 v[64:65], off
	v_mfma_f32_16x16x32_f16 v[190:193], v[44:47], v[48:51], v[190:193]
	v_lshl_add_u64 v[68:69], v[110:111], 0, v[94:95]
	s_mov_b32 m0, s68
	s_nop 0
	global_load_lds_dwordx4 v[68:69], off
	v_lshl_add_u64 v[72:73], v[112:113], 0, v[94:95]
	s_mov_b32 m0, s72
	s_nop 0
	global_load_lds_dwordx4 v[72:73], off
	v_mfma_f32_16x16x32_f16 v[44:47], v[44:47], v[56:59], v[210:213]
	s_nop 2
	ds_read_b128 v[210:213], v135 offset:51200
	v_mfma_f32_16x16x32_f16 v[154:157], v[52:55], v[32:35], v[154:157]
	v_lshl_add_u64 v[76:77], v[114:115], 0, v[94:95]
	s_mov_b32 m0, s64
	s_nop 0
	global_load_lds_dwordx4 v[76:77], off
	v_mfma_f32_16x16x32_f16 v[162:165], v[52:55], v[40:43], v[162:165]
	v_lshl_add_u64 v[80:81], v[116:117], 0, v[94:95]
	s_mov_b32 m0, s62
	s_nop 0
	global_load_lds_dwordx4 v[80:81], off
	s_waitcnt lgkmcnt(3)
	v_mfma_f32_16x16x32_f16 v[32:35], v[60:63], v[32:35], v[236:239]
	v_lshl_add_u64 v[84:85], v[118:119], 0, v[94:95]
	s_mov_b32 m0, s70
	s_nop 0
	global_load_lds_dwordx4 v[84:85], off
	v_mfma_f32_16x16x32_f16 v[40:43], v[60:63], v[40:43], v[206:209]
	s_nop 2
	ds_read_b128 v[206:209], v134 offset:18432
	v_mfma_f32_16x16x32_f16 v[194:197], v[52:55], v[48:51], v[194:197]
	v_lshl_add_u64 v[88:89], v[120:121], 0, v[94:95]
	s_mov_b32 m0, s74
	s_nop 0
	global_load_lds_dwordx4 v[88:89], off
	v_mfma_f32_16x16x32_f16 v[52:55], v[52:55], v[56:59], v[224:227]
	s_nop 2
	ds_read_b128 v[224:227], v135 offset:53248
	v_mfma_f32_16x16x32_f16 v[48:51], v[60:63], v[48:51], v[220:223]
	s_nop 2
	ds_read_b128 v[220:223], v134 offset:20480
	v_mfma_f32_16x16x32_f16 v[56:59], v[60:63], v[56:59], v[228:231]
	ds_read_b128 v[60:63], v134 offset:16384
	s_waitcnt lgkmcnt(0)
	v_mfma_f32_16x16x32_f16 v[138:141], v[202:205], v[60:63], v[138:141]
	ds_read_b128 v[228:231], v134 offset:22528
	v_lshl_add_u64 v[92:93], v[122:123], 0, v[94:95]
	s_mov_b32 m0, s66
	s_nop 0
	global_load_lds_dwordx4 v[92:93], off
	s_waitcnt vmcnt(0) lgkmcnt(0)
	s_barrier
; #define GL_LOAD(s_, kt_) if (VAR != 1) { a##s_##0 = GL_A(0, kt_); a##s_##1 = GL_A(1, kt_); a##s_##2 = GL_A(2, kt_); a##s_##3 = GL_A(3, kt_); b##s_##0 = GL_B(0, kt_); b##s_##1 = GL_B(1, kt_); b##s_##2 = GL_B(2, kt_); b##s_##3 = GL_B(3, kt_); }
; #define LDS_STORE(s_, buf_) if (VAR != 2) { LDS_ST1(sA, 0, buf_, a##s_##0) LDS_ST1(sA, 1, buf_, a##s_##1) LDS_ST1(sA, 2, buf_, a##s_##2) LDS_ST1(sA, 3, buf_, a##s_##3) LDS_ST1(sB, 0, buf_, b##s_##0) LDS_ST1(sB, 1, buf_, b##s_##1) LDS_ST1(sB, 2, buf_, b##s_##2) LDS_ST1(sB, 3, buf_, b##s_##3) }
;     ...
;   GL_LOAD(0, 0)
;   GL_LOAD(1, 1)
;   LDS_STORE(0, 0)
;   if (VAR != 4) __syncthreads();
; #pragma unroll
;   for (int kt = 0; kt < nk; kt += 2) {
;     if (kt + 2 < nk) { GL_LOAD(0, kt + 2) }
;     MMA_TILE(0)
;     LDS_STORE(1, 1)
;     if (VAR != 4) __syncthreads();
;     if (kt + 3 < nk) { GL_LOAD(1, kt + 3) }
;     MMA_TILE(1)
;     if (kt + 2 < nk) { LDS_STORE(0, 0) }
;     if (VAR != 4) __syncthreads();
	v_mfma_f32_16x16x32_f16 v[142:145], v[210:213], v[60:63], v[142:145]
	ds_read_b128 v[64:67], v133
	v_mfma_f32_16x16x32_f16 v[158:161], v[210:213], v[206:209], v[158:161]
	ds_read_b128 v[68:71], v136 offset:32768
	v_mfma_f32_16x16x32_f16 v[154:157], v[224:227], v[60:63], v[154:157]
	ds_read_b128 v[72:75], v133 offset:2048
	v_mfma_f32_16x16x32_f16 v[162:165], v[224:227], v[206:209], v[162:165]
	ds_read_b128 v[76:79], v136 offset:34816
	v_mfma_f32_16x16x32_f16 v[190:193], v[210:213], v[220:223], v[190:193]
	ds_read_b128 v[80:83], v133 offset:4096
	v_mfma_f32_16x16x32_f16 v[210:213], v[210:213], v[228:231], v[44:47]
	ds_read_b128 v[84:87], v136 offset:36864
	v_mfma_f32_16x16x32_f16 v[194:197], v[224:227], v[220:223], v[194:197]
	ds_read_b128 v[88:91], v133 offset:6144
	v_mfma_f32_16x16x32_f16 v[224:227], v[224:227], v[228:231], v[52:55]
	ds_read_b128 v[92:95], v136 offset:38912
	v_mfma_f32_16x16x32_f16 v[236:239], v[232:235], v[60:63], v[32:35]
	s_nop 0
	v_mfma_f32_16x16x32_f16 v[198:201], v[202:205], v[206:209], v[198:201]
	v_mfma_f32_16x16x32_f16 v[206:209], v[232:235], v[206:209], v[40:43]
	v_mfma_f32_16x16x32_f16 v[166:169], v[202:205], v[220:223], v[166:169]
	v_mfma_f32_16x16x32_f16 v[220:223], v[232:235], v[220:223], v[48:51]
	v_mfma_f32_16x16x32_f16 v[202:205], v[202:205], v[228:231], v[36:39]
	v_mfma_f32_16x16x32_f16 v[228:231], v[232:235], v[228:231], v[56:59]
	ds_read_b128 v[232:235], v135 offset:38912
	s_nop 1
	s_waitcnt lgkmcnt(7)
	v_mfma_f32_16x16x32_f16 v[138:141], v[68:71], v[64:67], v[138:141]
	s_waitcnt lgkmcnt(6)
	v_mfma_f32_16x16x32_f16 v[198:201], v[68:71], v[72:75], v[198:201]
	s_waitcnt lgkmcnt(5)
	v_mfma_f32_16x16x32_f16 v[142:145], v[76:79], v[64:67], v[142:145]
	v_mfma_f32_16x16x32_f16 v[158:161], v[76:79], v[72:75], v[158:161]
	s_waitcnt lgkmcnt(4)
	v_mfma_f32_16x16x32_f16 v[166:169], v[68:71], v[80:83], v[166:169]
	v_and_b32_e32 v10, 7, v148
	v_bfe_u32 v11, v148, 4, 3
	v_xor_b32_e32 v11, v11, v10
	v_sub_u32_e32 v11, v11, v10
	v_lshlrev_b32_e32 v10, 4, v11
	v_add_u32_e32 v10, 0x580, v10
	v_ashrrev_i32_e32 v11, 31, v10
	v_lshl_add_u64 v[28:29], v[108:109], 0, v[10:11]
	s_mov_b32 m0, s61
	s_nop 0
	global_load_lds_dwordx4 v[28:29], off
	s_waitcnt lgkmcnt(2)
	v_mfma_f32_16x16x32_f16 v[68:71], v[68:71], v[88:91], v[202:205]
	s_nop 2
	ds_read_b128 v[202:205], v135 offset:32768
	v_lshl_add_u64 v[24:25], v[110:111], 0, v[10:11]
	s_mov_b32 m0, s69
	s_nop 0
	global_load_lds_dwordx4 v[24:25], off
	v_mfma_f32_16x16x32_f16 v[190:193], v[76:79], v[80:83], v[190:193]
	v_lshl_add_u64 v[12:13], v[112:113], 0, v[10:11]
	s_mov_b32 m0, s73
	s_nop 0
	global_load_lds_dwordx4 v[12:13], off
	v_lshl_add_u64 v[16:17], v[114:115], 0, v[10:11]
	s_mov_b32 m0, s65
	s_nop 0
	global_load_lds_dwordx4 v[16:17], off
	v_mfma_f32_16x16x32_f16 v[76:79], v[76:79], v[88:91], v[210:213]
	s_nop 2
	ds_read_b128 v[210:213], v135 offset:34816
	v_mfma_f32_16x16x32_f16 v[154:157], v[84:87], v[64:67], v[154:157]
	v_lshl_add_u64 v[20:21], v[116:117], 0, v[10:11]
	s_mov_b32 m0, s63
	s_nop 0
	global_load_lds_dwordx4 v[20:21], off
	v_mfma_f32_16x16x32_f16 v[162:165], v[84:87], v[72:75], v[162:165]
	v_lshl_add_u64 v[0:1], v[118:119], 0, v[10:11]
	s_mov_b32 m0, s71
	s_nop 0
	global_load_lds_dwordx4 v[0:1], off
	s_waitcnt lgkmcnt(3)
	v_mfma_f32_16x16x32_f16 v[64:67], v[92:95], v[64:67], v[236:239]
	v_lshl_add_u64 v[4:5], v[120:121], 0, v[10:11]
	s_mov_b32 m0, s75
	s_nop 0
	global_load_lds_dwordx4 v[4:5], off
	v_mfma_f32_16x16x32_f16 v[72:75], v[92:95], v[72:75], v[206:209]
	s_nop 2
	ds_read_b128 v[206:209], v134 offset:2048
	v_mfma_f32_16x16x32_f16 v[194:197], v[84:87], v[80:83], v[194:197]
	v_lshl_add_u64 v[8:9], v[122:123], 0, v[10:11]
	s_mov_b32 m0, s67
	s_nop 0
	global_load_lds_dwordx4 v[8:9], off
	v_mfma_f32_16x16x32_f16 v[84:87], v[84:87], v[88:91], v[224:227]
	s_nop 2
	ds_read_b128 v[224:227], v135 offset:36864
	v_mfma_f32_16x16x32_f16 v[80:83], v[92:95], v[80:83], v[220:223]
	s_nop 2
	ds_read_b128 v[220:223], v134 offset:4096
	v_mfma_f32_16x16x32_f16 v[88:91], v[92:95], v[88:91], v[228:231]
	ds_read_b128 v[92:95], v134
	s_nop 1
	ds_read_b128 v[228:231], v134 offset:6144
	s_waitcnt vmcnt(0) lgkmcnt(0)
	s_barrier
	v_mfma_f32_16x16x32_f16 v[138:141], v[202:205], v[92:95], v[138:141]
	v_mfma_f32_16x16x32_f16 v[142:145], v[210:213], v[92:95], v[142:145]
	v_mfma_f32_16x16x32_f16 v[154:157], v[224:227], v[92:95], v[154:157]
	v_mfma_f32_16x16x32_f16 v[64:67], v[232:235], v[92:95], v[64:67]
	v_mfma_f32_16x16x32_f16 v[92:95], v[202:205], v[206:209], v[198:201]
	s_nop 2
	ds_read_b128 v[198:201], v133 offset:16384
	v_mfma_f32_16x16x32_f16 v[158:161], v[210:213], v[206:209], v[158:161]
	v_mfma_f32_16x16x32_f16 v[166:169], v[202:205], v[220:223], v[166:169]
	v_mfma_f32_16x16x32_f16 v[68:71], v[202:205], v[228:231], v[68:71]
	ds_read_b128 v[202:205], v136 offset:49152
	v_mfma_f32_16x16x32_f16 v[190:193], v[210:213], v[220:223], v[190:193]
	v_mfma_f32_16x16x32_f16 v[76:79], v[210:213], v[228:231], v[76:79]
	ds_read_b128 v[210:213], v136 offset:51200
	v_mfma_f32_16x16x32_f16 v[162:165], v[224:227], v[206:209], v[162:165]
	v_mfma_f32_16x16x32_f16 v[72:75], v[232:235], v[206:209], v[72:75]
	ds_read_b128 v[206:209], v133 offset:18432
	v_mfma_f32_16x16x32_f16 v[194:197], v[224:227], v[220:223], v[194:197]
	v_and_b32_e32 v38, 7, v148
	v_bfe_u32 v39, v148, 4, 3
	v_xor_b32_e32 v39, v39, v38
	v_sub_u32_e32 v39, v39, v38
	v_lshlrev_b32_e32 v38, 4, v39
	v_add_u32_e32 v38, 0x600, v38
	v_ashrrev_i32_e32 v39, 31, v38
	v_mfma_f32_16x16x32_f16 v[84:87], v[224:227], v[228:231], v[84:87]
	ds_read_b128 v[224:227], v136 offset:53248
	v_mfma_f32_16x16x32_f16 v[80:83], v[232:235], v[220:223], v[80:83]
	ds_read_b128 v[220:223], v133 offset:20480
	v_mfma_f32_16x16x32_f16 v[88:91], v[232:235], v[228:231], v[88:91]
	ds_read_b128 v[228:231], v133 offset:22528
	s_waitcnt lgkmcnt(5)
; #define GL_LOAD(s_, kt_) if (VAR != 1) { a##s_##0 = GL_A(0, kt_); a##s_##1 = GL_A(1, kt_); a##s_##2 = GL_A(2, kt_); a##s_##3 = GL_A(3, kt_); b##s_##0 = GL_B(0, kt_); b##s_##1 = GL_B(1, kt_); b##s_##2 = GL_B(2, kt_); b##s_##3 = GL_B(3, kt_); }
; #define LDS_STORE(s_, buf_) if (VAR != 2) { LDS_ST1(sA, 0, buf_, a##s_##0) LDS_ST1(sA, 1, buf_, a##s_##1) LDS_ST1(sA, 2, buf_, a##s_##2) LDS_ST1(sA, 3, buf_, a##s_##3) LDS_ST1(sB, 0, buf_, b##s_##0) LDS_ST1(sB, 1, buf_, b##s_##1) LDS_ST1(sB, 2, buf_, b##s_##2) LDS_ST1(sB, 3, buf_, b##s_##3) }
;     ...
;   GL_LOAD(0, 0)
;   GL_LOAD(1, 1)
;   LDS_STORE(0, 0)
;   if (VAR != 4) __syncthreads();
; #pragma unroll
;   for (int kt = 0; kt < nk; kt += 2) {
;     if (kt + 2 < nk) { GL_LOAD(0, kt + 2) }
;     MMA_TILE(0)
;     LDS_STORE(1, 1)
;     if (VAR != 4) __syncthreads();
;     if (kt + 3 < nk) { GL_LOAD(1, kt + 3) }
;     MMA_TILE(1)
;     if (kt + 2 < nk) { LDS_STORE(0, 0) }
;     if (VAR != 4) __syncthreads();
	v_mfma_f32_16x16x32_f16 v[138:141], v[202:205], v[198:201], v[138:141]
	ds_read_b128 v[232:235], v136 offset:55296
	s_waitcnt lgkmcnt(4)
	v_mfma_f32_16x16x32_f16 v[92:95], v[202:205], v[206:209], v[92:95]
	v_lshl_add_u64 v[52:53], v[108:109], 0, v[38:39]
	s_mov_b32 m0, s60
	s_nop 0
	global_load_lds_dwordx4 v[52:53], off
	v_mfma_f32_16x16x32_f16 v[142:145], v[210:213], v[198:201], v[142:145]
	v_lshl_add_u64 v[56:57], v[110:111], 0, v[38:39]
	s_mov_b32 m0, s68
	s_nop 0
	global_load_lds_dwordx4 v[56:57], off
	v_mfma_f32_16x16x32_f16 v[158:161], v[210:213], v[206:209], v[158:161]
	v_lshl_add_u64 v[60:61], v[112:113], 0, v[38:39]
	s_mov_b32 m0, s72
	s_nop 0
	global_load_lds_dwordx4 v[60:61], off
	s_waitcnt lgkmcnt(2)
	v_mfma_f32_16x16x32_f16 v[166:169], v[202:205], v[220:223], v[166:169]
	v_lshl_add_u64 v[40:41], v[114:115], 0, v[38:39]
	s_mov_b32 m0, s64
	s_nop 0
	global_load_lds_dwordx4 v[40:41], off
	s_waitcnt lgkmcnt(1)
	v_mfma_f32_16x16x32_f16 v[68:71], v[202:205], v[228:231], v[68:71]
	ds_read_b128 v[202:205], v135 offset:49152
	v_mfma_f32_16x16x32_f16 v[190:193], v[210:213], v[220:223], v[190:193]
	v_lshl_add_u64 v[44:45], v[116:117], 0, v[38:39]
	s_mov_b32 m0, s62
	s_nop 0
	global_load_lds_dwordx4 v[44:45], off
	v_mfma_f32_16x16x32_f16 v[76:79], v[210:213], v[228:231], v[76:79]
	ds_read_b128 v[210:213], v135 offset:51200
	v_mfma_f32_16x16x32_f16 v[154:157], v[224:227], v[198:201], v[154:157]
	v_lshl_add_u64 v[48:49], v[118:119], 0, v[38:39]
	s_mov_b32 m0, s70
	s_nop 0
	global_load_lds_dwordx4 v[48:49], off
	v_mfma_f32_16x16x32_f16 v[162:165], v[224:227], v[206:209], v[162:165]
	v_lshl_add_u64 v[32:33], v[120:121], 0, v[38:39]
	s_mov_b32 m0, s74
	s_nop 0
	global_load_lds_dwordx4 v[32:33], off
	s_waitcnt lgkmcnt(2)
	v_mfma_f32_16x16x32_f16 v[64:67], v[232:235], v[198:201], v[64:67]
	ds_read_b128 v[198:201], v134 offset:16384
	v_mfma_f32_16x16x32_f16 v[72:75], v[232:235], v[206:209], v[72:75]
	ds_read_b128 v[206:209], v134 offset:18432
	v_mfma_f32_16x16x32_f16 v[194:197], v[224:227], v[220:223], v[194:197]
	v_lshl_add_u64 v[36:37], v[122:123], 0, v[38:39]
	s_mov_b32 m0, s66
	s_nop 0
	global_load_lds_dwordx4 v[36:37], off
	v_mfma_f32_16x16x32_f16 v[84:87], v[224:227], v[228:231], v[84:87]
	ds_read_b128 v[224:227], v135 offset:53248
	v_mfma_f32_16x16x32_f16 v[80:83], v[232:235], v[220:223], v[80:83]
	ds_read_b128 v[220:223], v134 offset:20480
	v_mfma_f32_16x16x32_f16 v[88:91], v[232:235], v[228:231], v[88:91]
	ds_read_b128 v[228:231], v134 offset:22528
	ds_read_b128 v[232:235], v135 offset:55296
	s_waitcnt vmcnt(0) lgkmcnt(0)
	s_barrier
	v_mfma_f32_16x16x32_f16 v[138:141], v[202:205], v[198:201], v[138:141]
	v_and_b32_e32 v6, 7, v148
	v_bfe_u32 v7, v148, 4, 3
	v_xor_b32_e32 v7, v7, v6
	v_sub_u32_e32 v7, v7, v6
	v_lshlrev_b32_e32 v6, 4, v7
	v_add_u32_e32 v6, 0x680, v6
	v_ashrrev_i32_e32 v7, 31, v6
	v_mfma_f32_16x16x32_f16 v[92:95], v[202:205], v[206:209], v[92:95]
	global_load_dwordx4 v[60:63], v[108:109], off offset:1792
	v_mfma_f32_16x16x32_f16 v[142:145], v[210:213], v[198:201], v[142:145]
	global_load_dwordx4 v[48:51], v[110:111], off offset:1792
	v_mfma_f32_16x16x32_f16 v[158:161], v[210:213], v[206:209], v[158:161]
	global_load_dwordx4 v[52:55], v[112:113], off offset:1792
	v_mfma_f32_16x16x32_f16 v[166:169], v[202:205], v[220:223], v[166:169]
	global_load_dwordx4 v[56:59], v[114:115], off offset:1792
	v_mfma_f32_16x16x32_f16 v[68:71], v[202:205], v[228:231], v[68:71]
	ds_read_b128 v[202:205], v136 offset:32768
	v_mfma_f32_16x16x32_f16 v[190:193], v[210:213], v[220:223], v[190:193]
	global_load_dwordx4 v[36:39], v[116:117], off offset:1792
	v_mfma_f32_16x16x32_f16 v[76:79], v[210:213], v[228:231], v[76:79]
	ds_read_b128 v[210:213], v136 offset:34816
	v_mfma_f32_16x16x32_f16 v[154:157], v[224:227], v[198:201], v[154:157]
	global_load_dwordx4 v[40:43], v[118:119], off offset:1792
	v_mfma_f32_16x16x32_f16 v[162:165], v[224:227], v[206:209], v[162:165]
	global_load_dwordx4 v[44:47], v[120:121], off offset:1792
	v_mfma_f32_16x16x32_f16 v[64:67], v[232:235], v[198:201], v[64:67]
	ds_read_b128 v[198:201], v133
	v_mfma_f32_16x16x32_f16 v[72:75], v[232:235], v[206:209], v[72:75]
	ds_read_b128 v[206:209], v133 offset:2048
	v_mfma_f32_16x16x32_f16 v[194:197], v[224:227], v[220:223], v[194:197]
	global_load_dwordx4 v[32:35], v[122:123], off offset:1792
	v_mfma_f32_16x16x32_f16 v[84:87], v[224:227], v[228:231], v[84:87]
	ds_read_b128 v[224:227], v136 offset:36864
	v_mfma_f32_16x16x32_f16 v[80:83], v[232:235], v[220:223], v[80:83]
	ds_read_b128 v[220:223], v133 offset:4096
	v_mfma_f32_16x16x32_f16 v[88:91], v[232:235], v[228:231], v[88:91]
	ds_read_b128 v[228:231], v133 offset:6144
	s_waitcnt lgkmcnt(4)
	v_mfma_f32_16x16x32_f16 v[138:141], v[202:205], v[198:201], v[138:141]
	ds_read_b128 v[232:235], v136 offset:38912
	s_waitcnt lgkmcnt(4)
	v_mfma_f32_16x16x32_f16 v[92:95], v[202:205], v[206:209], v[92:95]
	v_lshl_add_u64 v[20:21], v[108:109], 0, v[6:7]
	s_mov_b32 m0, s61
	s_nop 0
	global_load_lds_dwordx4 v[20:21], off
	v_mfma_f32_16x16x32_f16 v[142:145], v[210:213], v[198:201], v[142:145]
	v_lshl_add_u64 v[24:25], v[110:111], 0, v[6:7]
	s_mov_b32 m0, s69
	s_nop 0
	global_load_lds_dwordx4 v[24:25], off
	v_mfma_f32_16x16x32_f16 v[158:161], v[210:213], v[206:209], v[158:161]
	v_lshl_add_u64 v[28:29], v[112:113], 0, v[6:7]
	s_mov_b32 m0, s73
	s_nop 0
	global_load_lds_dwordx4 v[28:29], off
	s_waitcnt lgkmcnt(2)
	v_mfma_f32_16x16x32_f16 v[166:169], v[202:205], v[220:223], v[166:169]
	v_lshl_add_u64 v[8:9], v[114:115], 0, v[6:7]
	s_mov_b32 m0, s65
	s_nop 0
	global_load_lds_dwordx4 v[8:9], off
	s_waitcnt lgkmcnt(1)
; #define GL_LOAD(s_, kt_) if (VAR != 1) { a##s_##0 = GL_A(0, kt_); a##s_##1 = GL_A(1, kt_); a##s_##2 = GL_A(2, kt_); a##s_##3 = GL_A(3, kt_); b##s_##0 = GL_B(0, kt_); b##s_##1 = GL_B(1, kt_); b##s_##2 = GL_B(2, kt_); b##s_##3 = GL_B(3, kt_); }
; #define LDS_STORE(s_, buf_) if (VAR != 2) { LDS_ST1(sA, 0, buf_, a##s_##0) LDS_ST1(sA, 1, buf_, a##s_##1) LDS_ST1(sA, 2, buf_, a##s_##2) LDS_ST1(sA, 3, buf_, a##s_##3) LDS_ST1(sB, 0, buf_, b##s_##0) LDS_ST1(sB, 1, buf_, b##s_##1) LDS_ST1(sB, 2, buf_, b##s_##2) LDS_ST1(sB, 3, buf_, b##s_##3) }
;     ...
;   GL_LOAD(0, 0)
;   GL_LOAD(1, 1)
;   LDS_STORE(0, 0)
;   if (VAR != 4) __syncthreads();
; #pragma unroll
;   for (int kt = 0; kt < nk; kt += 2) {
;     if (kt + 2 < nk) { GL_LOAD(0, kt + 2) }
;     MMA_TILE(0)
;     LDS_STORE(1, 1)
;     if (VAR != 4) __syncthreads();
;     if (kt + 3 < nk) { GL_LOAD(1, kt + 3) }
;     MMA_TILE(1)
;     if (kt + 2 < nk) { LDS_STORE(0, 0) }
;     if (VAR != 4) __syncthreads();
	v_mfma_f32_16x16x32_f16 v[68:71], v[202:205], v[228:231], v[68:71]
	ds_read_b128 v[202:205], v135 offset:32768
	v_mfma_f32_16x16x32_f16 v[190:193], v[210:213], v[220:223], v[190:193]
	v_lshl_add_u64 v[12:13], v[116:117], 0, v[6:7]
	s_mov_b32 m0, s63
	s_nop 0
	global_load_lds_dwordx4 v[12:13], off
	v_mfma_f32_16x16x32_f16 v[76:79], v[210:213], v[228:231], v[76:79]
	ds_read_b128 v[210:213], v135 offset:34816
	v_mfma_f32_16x16x32_f16 v[154:157], v[224:227], v[198:201], v[154:157]
	v_lshl_add_u64 v[16:17], v[118:119], 0, v[6:7]
	s_mov_b32 m0, s71
	s_nop 0
	global_load_lds_dwordx4 v[16:17], off
	v_mfma_f32_16x16x32_f16 v[162:165], v[224:227], v[206:209], v[162:165]
	v_lshl_add_u64 v[0:1], v[120:121], 0, v[6:7]
	s_mov_b32 m0, s75
	s_nop 0
	global_load_lds_dwordx4 v[0:1], off
	s_waitcnt lgkmcnt(2)
	v_mfma_f32_16x16x32_f16 v[64:67], v[232:235], v[198:201], v[64:67]
	ds_read_b128 v[198:201], v134
	v_mfma_f32_16x16x32_f16 v[72:75], v[232:235], v[206:209], v[72:75]
	ds_read_b128 v[206:209], v134 offset:2048
	v_mfma_f32_16x16x32_f16 v[194:197], v[224:227], v[220:223], v[194:197]
	v_lshl_add_u64 v[4:5], v[122:123], 0, v[6:7]
	s_mov_b32 m0, s67
	s_nop 0
	global_load_lds_dwordx4 v[4:5], off
	v_mfma_f32_16x16x32_f16 v[84:87], v[224:227], v[228:231], v[84:87]
	ds_read_b128 v[224:227], v135 offset:36864
	v_mfma_f32_16x16x32_f16 v[80:83], v[232:235], v[220:223], v[80:83]
	ds_read_b128 v[220:223], v134 offset:4096
	v_mfma_f32_16x16x32_f16 v[88:91], v[232:235], v[228:231], v[88:91]
	ds_read_b128 v[228:231], v134 offset:6144
	ds_read_b128 v[232:235], v135 offset:38912
	s_waitcnt vmcnt(0) lgkmcnt(0)
	s_barrier
	v_mfma_f32_16x16x32_f16 v[138:141], v[202:205], v[198:201], v[138:141]
	global_load_dwordx4 v[28:31], v[108:109], off offset:1920
	v_mfma_f32_16x16x32_f16 v[92:95], v[202:205], v[206:209], v[92:95]
	global_load_dwordx4 v[16:19], v[110:111], off offset:1920
	v_mfma_f32_16x16x32_f16 v[142:145], v[210:213], v[198:201], v[142:145]
	ds_read_b128 v[108:111], v133 offset:16384
	v_mfma_f32_16x16x32_f16 v[158:161], v[210:213], v[206:209], v[158:161]
	global_load_dwordx4 v[20:23], v[112:113], off offset:1920
	v_mfma_f32_16x16x32_f16 v[166:169], v[202:205], v[220:223], v[166:169]
	global_load_dwordx4 v[24:27], v[114:115], off offset:1920
	v_mfma_f32_16x16x32_f16 v[68:71], v[202:205], v[228:231], v[68:71]
	ds_read_b128 v[112:115], v136 offset:49152
	v_mfma_f32_16x16x32_f16 v[190:193], v[210:213], v[220:223], v[190:193]
	ds_read_b128 v[202:205], v136 offset:53248
	v_mfma_f32_16x16x32_f16 v[76:79], v[210:213], v[228:231], v[76:79]
	ds_read_b128 v[210:213], v136 offset:55296
	v_mfma_f32_16x16x32_f16 v[154:157], v[224:227], v[198:201], v[154:157]
	global_load_dwordx4 v[4:7], v[116:117], off offset:1920
	v_mfma_f32_16x16x32_f16 v[162:165], v[224:227], v[206:209], v[162:165]
	global_load_dwordx4 v[8:11], v[118:119], off offset:1920
	v_mfma_f32_16x16x32_f16 v[64:67], v[232:235], v[198:201], v[64:67]
	ds_read_b128 v[116:119], v133 offset:18432
	v_mfma_f32_16x16x32_f16 v[72:75], v[232:235], v[206:209], v[72:75]
	ds_read_b128 v[198:201], v133 offset:20480
	v_mfma_f32_16x16x32_f16 v[194:197], v[224:227], v[220:223], v[194:197]
	ds_read_b128 v[206:209], v133 offset:22528
	v_mfma_f32_16x16x32_f16 v[84:87], v[224:227], v[228:231], v[84:87]
	global_load_dwordx4 v[12:15], v[120:121], off offset:1920
	v_mfma_f32_16x16x32_f16 v[80:83], v[232:235], v[220:223], v[80:83]
	global_load_dwordx4 v[0:3], v[122:123], off offset:1920
	v_mfma_f32_16x16x32_f16 v[88:91], v[232:235], v[228:231], v[88:91]
	ds_read_b128 v[120:123], v136 offset:51200
	s_waitcnt lgkmcnt(6)
	v_mfma_f32_16x16x32_f16 v[138:141], v[112:115], v[108:111], v[138:141]
	ds_write_b128 v101, v[60:63]
	s_waitcnt lgkmcnt(4)
	v_mfma_f32_16x16x32_f16 v[92:95], v[112:115], v[116:119], v[92:95]
	ds_write_b128 v131, v[48:51]
	s_waitcnt lgkmcnt(2)
	v_mfma_f32_16x16x32_f16 v[142:145], v[120:123], v[108:111], v[142:145]
	ds_write_b128 v132, v[52:55]
	v_mfma_f32_16x16x32_f16 v[154:157], v[202:205], v[108:111], v[154:157]
	v_mfma_f32_16x16x32_f16 v[64:67], v[210:213], v[108:111], v[64:67]
	v_mfma_f32_16x16x32_f16 v[108:111], v[120:123], v[116:119], v[158:161]
	ds_write_b128 v130, v[56:59]
	v_mfma_f32_16x16x32_f16 v[158:161], v[202:205], v[116:119], v[162:165]
	v_mfma_f32_16x16x32_f16 v[72:75], v[210:213], v[116:119], v[72:75]
	v_mfma_f32_16x16x32_f16 v[116:119], v[112:115], v[198:201], v[166:169]
	ds_write_b128 v101, v[36:39] offset:32768
	ds_write_b128 v131, v[40:43] offset:32768
	v_mfma_f32_16x16x32_f16 v[68:71], v[112:115], v[206:209], v[68:71]
	ds_read_b128 v[112:115], v134 offset:16384
	ds_write_b128 v132, v[44:47] offset:32768
	v_mfma_f32_16x16x32_f16 v[162:165], v[120:123], v[198:201], v[190:193]
	s_nop 2
	ds_read_b128 v[190:193], v134 offset:18432
	v_mfma_f32_16x16x32_f16 v[76:79], v[120:123], v[206:209], v[76:79]
	ds_read_b128 v[120:123], v135 offset:49152
	ds_write_b128 v130, v[32:35] offset:32768
	v_mfma_f32_16x16x32_f16 v[166:169], v[202:205], v[198:201], v[194:197]
	s_nop 2
	ds_read_b128 v[194:197], v135 offset:51200
	v_mfma_f32_16x16x32_f16 v[84:87], v[202:205], v[206:209], v[84:87]
	ds_read_b128 v[202:205], v135 offset:53248
	v_mfma_f32_16x16x32_f16 v[80:83], v[210:213], v[198:201], v[80:83]
	ds_read_b128 v[198:201], v134 offset:20480
	v_mfma_f32_16x16x32_f16 v[88:91], v[210:213], v[206:209], v[88:91]
	ds_read_b128 v[206:209], v134 offset:22528
	s_waitcnt lgkmcnt(5)
	v_mfma_f32_16x16x32_f16 v[138:141], v[120:123], v[112:115], v[138:141]
	ds_read_b128 v[210:213], v135 offset:55296
	s_waitcnt lgkmcnt(0)
	s_barrier
; #define GL_LOAD(s_, kt_) if (VAR != 1) { a##s_##0 = GL_A(0, kt_); a##s_##1 = GL_A(1, kt_); a##s_##2 = GL_A(2, kt_); a##s_##3 = GL_A(3, kt_); b##s_##0 = GL_B(0, kt_); b##s_##1 = GL_B(1, kt_); b##s_##2 = GL_B(2, kt_); b##s_##3 = GL_B(3, kt_); }
; #define LDS_STORE(s_, buf_) if (VAR != 2) { LDS_ST1(sA, 0, buf_, a##s_##0) LDS_ST1(sA, 1, buf_, a##s_##1) LDS_ST1(sA, 2, buf_, a##s_##2) LDS_ST1(sA, 3, buf_, a##s_##3) LDS_ST1(sB, 0, buf_, b##s_##0) LDS_ST1(sB, 1, buf_, b##s_##1) LDS_ST1(sB, 2, buf_, b##s_##2) LDS_ST1(sB, 3, buf_, b##s_##3) }
;     ...
;   GL_LOAD(0, 0)
;   GL_LOAD(1, 1)
;   LDS_STORE(0, 0)
;   if (VAR != 4) __syncthreads();
; #pragma unroll
;   for (int kt = 0; kt < nk; kt += 2) {
;     if (kt + 2 < nk) { GL_LOAD(0, kt + 2) }
;     MMA_TILE(0)
;     LDS_STORE(1, 1)
;     if (VAR != 4) __syncthreads();
;     if (kt + 3 < nk) { GL_LOAD(1, kt + 3) }
;     MMA_TILE(1)
;     if (kt + 2 < nk) { LDS_STORE(0, 0) }
;     if (VAR != 4) __syncthreads();
	v_mfma_f32_16x16x32_f16 v[142:145], v[194:197], v[112:115], v[142:145]
	ds_read_b128 v[32:35], v133
	v_mfma_f32_16x16x32_f16 v[108:111], v[194:197], v[190:193], v[108:111]
	ds_read_b128 v[36:39], v136 offset:32768
	v_mfma_f32_16x16x32_f16 v[154:157], v[202:205], v[112:115], v[154:157]
	ds_read_b128 v[40:43], v133 offset:2048
	v_mfma_f32_16x16x32_f16 v[64:67], v[210:213], v[112:115], v[64:67]
	v_mfma_f32_16x16x32_f16 v[112:115], v[202:205], v[190:193], v[158:161]
	ds_read_b128 v[44:47], v136 offset:34816
	v_mfma_f32_16x16x32_f16 v[158:161], v[194:197], v[198:201], v[162:165]
	ds_read_b128 v[48:51], v133 offset:4096
	v_mfma_f32_16x16x32_f16 v[76:79], v[194:197], v[206:209], v[76:79]
	ds_read_b128 v[52:55], v136 offset:36864
	v_mfma_f32_16x16x32_f16 v[162:165], v[202:205], v[198:201], v[166:169]
	ds_read_b128 v[56:59], v133 offset:6144
	v_mfma_f32_16x16x32_f16 v[84:87], v[202:205], v[206:209], v[84:87]
	ds_read_b128 v[60:63], v136 offset:38912
	s_waitcnt vmcnt(7)
	ds_write_b128 v101, v[28:31] offset:16384
	v_mfma_f32_16x16x32_f16 v[72:75], v[210:213], v[190:193], v[72:75]
	s_waitcnt vmcnt(6)
	ds_write_b128 v131, v[16:19] offset:16384
	v_mfma_f32_16x16x32_f16 v[92:95], v[120:123], v[190:193], v[92:95]
	s_waitcnt vmcnt(5)
	ds_write_b128 v132, v[20:23] offset:16384
	v_mfma_f32_16x16x32_f16 v[80:83], v[210:213], v[198:201], v[80:83]
	s_waitcnt vmcnt(4)
	ds_write_b128 v130, v[24:27] offset:16384
	v_mfma_f32_16x16x32_f16 v[88:91], v[210:213], v[206:209], v[88:91]
	s_waitcnt vmcnt(3)
	ds_write_b128 v101, v[4:7] offset:49152
	v_mfma_f32_16x16x32_f16 v[116:119], v[120:123], v[198:201], v[116:119]
	s_waitcnt vmcnt(2)
	ds_write_b128 v131, v[8:11] offset:49152
	v_mfma_f32_16x16x32_f16 v[68:71], v[120:123], v[206:209], v[68:71]
	s_waitcnt vmcnt(1)
	ds_write_b128 v132, v[12:15] offset:49152
	s_waitcnt lgkmcnt(13)
	v_mfma_f32_16x16x32_f16 v[120:123], v[36:39], v[32:35], v[138:141]
	s_waitcnt vmcnt(0)
	ds_write_b128 v130, v[0:3] offset:49152
	s_waitcnt lgkmcnt(12)
	v_mfma_f32_16x16x32_f16 v[138:141], v[44:47], v[32:35], v[142:145]
	s_waitcnt lgkmcnt(10)
	v_mfma_f32_16x16x32_f16 v[142:145], v[52:55], v[32:35], v[154:157]
	s_waitcnt lgkmcnt(8)
	v_mfma_f32_16x16x32_f16 v[32:35], v[60:63], v[32:35], v[64:67]
	v_mfma_f32_16x16x32_f16 v[64:67], v[36:39], v[40:43], v[92:95]
	ds_read_b128 v[154:157], v134 offset:6144
	v_mfma_f32_16x16x32_f16 v[92:95], v[44:47], v[40:43], v[108:111]
	v_mfma_f32_16x16x32_f16 v[108:111], v[52:55], v[40:43], v[112:115]
	v_mfma_f32_16x16x32_f16 v[40:43], v[60:63], v[40:43], v[72:75]
	v_mfma_f32_16x16x32_f16 v[72:75], v[36:39], v[48:51], v[116:119]
	v_mfma_f32_16x16x32_f16 v[36:39], v[36:39], v[56:59], v[68:71]
	s_nop 2
	ds_read_b128 v[68:71], v135 offset:32768
	v_mfma_f32_16x16x32_f16 v[112:115], v[44:47], v[48:51], v[158:161]
	s_nop 2
	ds_read_b128 v[158:161], v135 offset:38912
	v_mfma_f32_16x16x32_f16 v[44:47], v[44:47], v[56:59], v[76:79]
	s_nop 2
	ds_read_b128 v[76:79], v134 offset:2048
	v_mfma_f32_16x16x32_f16 v[116:119], v[52:55], v[48:51], v[162:165]
	v_mfma_f32_16x16x32_f16 v[52:55], v[52:55], v[56:59], v[84:87]
	s_nop 2
	ds_read_b128 v[84:87], v134 offset:4096
	v_mfma_f32_16x16x32_f16 v[48:51], v[60:63], v[48:51], v[80:83]
	s_nop 2
	ds_read_b128 v[80:83], v135 offset:34816
	v_mfma_f32_16x16x32_f16 v[56:59], v[60:63], v[56:59], v[88:91]
	ds_read_b128 v[60:63], v134
	s_waitcnt lgkmcnt(0)
	v_mfma_f32_16x16x32_f16 v[120:123], v[68:71], v[60:63], v[120:123]
	ds_read_b128 v[88:91], v135 offset:36864
	s_waitcnt lgkmcnt(0)
	s_barrier
	v_mfma_f32_16x16x32_f16 v[138:141], v[80:83], v[60:63], v[138:141]
	ds_read_b128 v[0:3], v133 offset:16384
	v_mfma_f32_16x16x32_f16 v[142:145], v[88:91], v[60:63], v[142:145]
	v_mfma_f32_16x16x32_f16 v[32:35], v[158:161], v[60:63], v[32:35]
	v_mfma_f32_16x16x32_f16 v[60:63], v[68:71], v[76:79], v[64:67]
	v_mfma_f32_16x16x32_f16 v[64:67], v[80:83], v[76:79], v[92:95]
	ds_read_b128 v[4:7], v136 offset:49152
	ds_read_b128 v[8:11], v133 offset:18432
	v_mfma_f32_16x16x32_f16 v[92:95], v[88:91], v[76:79], v[108:111]
	ds_read_b128 v[12:15], v136 offset:51200
	v_mfma_f32_16x16x32_f16 v[40:43], v[158:161], v[76:79], v[40:43]
	v_mfma_f32_16x16x32_f16 v[76:79], v[80:83], v[84:87], v[112:115]
	ds_read_b128 v[16:19], v133 offset:20480
	v_mfma_f32_16x16x32_f16 v[44:47], v[80:83], v[154:157], v[44:47]
	ds_read_b128 v[20:23], v136 offset:53248
	v_mfma_f32_16x16x32_f16 v[108:111], v[88:91], v[84:87], v[116:119]
	ds_read_b128 v[24:27], v133 offset:22528
	v_mfma_f32_16x16x32_f16 v[52:55], v[88:91], v[154:157], v[52:55]
	ds_read_b128 v[28:31], v136 offset:55296
	ds_read_b128 v[112:115], v135 offset:53248
	ds_read_b128 v[116:119], v134 offset:22528
	v_ashrrev_i32_e32 v101, 31, v100
	v_mfma_f32_16x16x32_f16 v[48:51], v[158:161], v[84:87], v[48:51]
	v_mfma_f32_16x16x32_f16 v[56:59], v[158:161], v[154:157], v[56:59]
	v_mfma_f32_16x16x32_f16 v[72:75], v[68:71], v[84:87], v[72:75]
	v_mfma_f32_16x16x32_f16 v[36:39], v[68:71], v[154:157], v[36:39]
	s_waitcnt lgkmcnt(8)
	v_mfma_f32_16x16x32_f16 v[68:71], v[4:7], v[0:3], v[120:123]
	s_nop 2
	ds_read_b128 v[120:123], v135 offset:55296
	s_waitcnt lgkmcnt(7)
	v_mfma_f32_16x16x32_f16 v[80:83], v[12:15], v[0:3], v[138:141]
	s_waitcnt lgkmcnt(5)
	v_mfma_f32_16x16x32_f16 v[84:87], v[20:23], v[0:3], v[142:145]
	s_waitcnt lgkmcnt(3)
	v_mfma_f32_16x16x32_f16 v[0:3], v[28:31], v[0:3], v[32:35]
	v_mfma_f32_16x16x32_f16 v[32:35], v[4:7], v[8:11], v[60:63]
	v_mfma_f32_16x16x32_f16 v[60:63], v[12:15], v[8:11], v[64:67]
	v_mfma_f32_16x16x32_f16 v[72:75], v[4:7], v[16:19], v[72:75]
	v_mfma_f32_16x16x32_f16 v[76:79], v[12:15], v[16:19], v[76:79]
	v_mfma_f32_16x16x32_f16 v[44:47], v[12:15], v[24:27], v[44:47]
	ds_read_b128 v[12:15], v134 offset:16384
	v_mfma_f32_16x16x32_f16 v[64:67], v[20:23], v[8:11], v[92:95]
	s_nop 2
	ds_read_b128 v[92:95], v135 offset:51200
	v_mfma_f32_16x16x32_f16 v[88:91], v[20:23], v[16:19], v[108:111]
	s_nop 2
	ds_read_b128 v[108:111], v134 offset:20480
	v_mfma_f32_16x16x32_f16 v[16:19], v[28:31], v[16:19], v[48:51]
	v_mfma_f32_16x16x32_f16 v[48:51], v[20:23], v[24:27], v[52:55]
	ds_read_b128 v[20:23], v134 offset:18432
	v_mfma_f32_16x16x32_f16 v[52:55], v[28:31], v[24:27], v[56:59]
	s_nop 2
	ds_read_b128 v[56:59], v135 offset:49152
	s_waitcnt lgkmcnt(0)
	s_barrier
; DI unsigned pack2(float lo, float hi) { f2_t v = {lo, hi}; h2_t b = __builtin_convertvector(v, h2_t); return __builtin_bit_cast(unsigned, b); }
; template <int VAR> DI void phase_up(const Params& P, int l, char* smem) {
;     ...
; #pragma unroll
;     for (int mt = 0; mt < 4; ++mt) {
;       const int row = row0 + mt * 16 + lr;
; #pragma unroll
;       for (int nt = 0; nt < 4; ++nt) {
;         float v[4];
; #pragma unroll
;         for (int j = 0; j < 4; ++j) { const float a = fmaxf(acc[mt][nt][j] * rs[mt], 0.f); v[j] = a * a; }
;         *(uint2*)(U + (size_t)row * DFF + col0 + nt * 16 + 4 * g) = make_uint2(pack2(v[0], v[1]), pack2(v[2], v[3]));
;       }
	s_setprio 0
	v_readlane_b32 s60, v255, 0
	v_readlane_b32 s61, v255, 1
	v_readlane_b32 s62, v255, 2
	v_readlane_b32 s63, v255, 3
	v_readlane_b32 s64, v255, 4
	v_readlane_b32 s65, v255, 5
	v_readlane_b32 s66, v255, 6
	v_readlane_b32 s67, v255, 7
	v_readlane_b32 s68, v255, 8
	v_readlane_b32 s69, v255, 9
	v_readlane_b32 s70, v255, 10
	v_readlane_b32 s71, v255, 11
	v_readlane_b32 s72, v255, 12
	v_readlane_b32 s73, v255, 13
	v_readlane_b32 s74, v255, 14
	v_readlane_b32 s75, v255, 15
	s_nop 4
	v_mfma_f32_16x16x32_f16 v[4:7], v[4:7], v[24:27], v[36:39]
	v_mfma_f32_16x16x32_f16 v[68:71], v[56:59], v[12:15], v[68:71]
	v_mfma_f32_16x16x32_f16 v[8:11], v[28:31], v[8:11], v[40:43]
	v_mfma_f32_16x16x32_f16 v[80:83], v[92:95], v[12:15], v[80:83]
	v_mfma_f32_16x16x32_f16 v[84:87], v[112:115], v[12:15], v[84:87]
	v_mfma_f32_16x16x32_f16 v[130:133], v[120:123], v[12:15], v[0:3]
	v_mfma_f32_16x16x32_f16 v[12:15], v[56:59], v[116:119], v[4:7]
	v_mfma_f32_16x16x32_f16 v[4:7], v[112:115], v[116:119], v[48:51]
	v_mfma_f32_16x16x32_f16 v[134:137], v[56:59], v[20:23], v[32:35]
	v_mfma_f32_16x16x32_f16 v[32:35], v[120:123], v[20:23], v[8:11]
	v_mfma_f32_16x16x32_f16 v[8:11], v[92:95], v[116:119], v[44:47]
	v_mfma_f32_16x16x32_f16 v[16:19], v[120:123], v[108:111], v[16:19]
	v_mfma_f32_16x16x32_f16 v[40:43], v[92:95], v[20:23], v[60:63]
	v_mfma_f32_16x16x32_f16 v[36:39], v[112:115], v[20:23], v[64:67]
	v_mfma_f32_16x16x32_f16 v[28:31], v[56:59], v[108:111], v[72:75]
	v_mfma_f32_16x16x32_f16 v[24:27], v[92:95], v[108:111], v[76:79]
	v_mfma_f32_16x16x32_f16 v[20:23], v[112:115], v[108:111], v[88:91]
	v_mfma_f32_16x16x32_f16 v[0:3], v[120:123], v[116:119], v[52:55]
	v_lshl_add_u64 v[92:93], v[100:101], 1, v[96:97]
	v_and_b32_e32 v76, 16, v148
	v_lshrrev_b32_e32 v77, 1, v76
	v_add_u32_e32 v76, v76, v77
	v_and_b32_e32 v77, 8, v148
	v_lshl_add_u32 v76, v77, 3, v76
	v_lshlrev_b32_e32 v77, 13, v77
	v_sub_u32_e32 v76, v76, v77
	v_ashrrev_i32_e32 v77, 31, v76
	v_lshl_add_u64 v[92:93], v[76:77], 0, v[92:93]
	v_mov_b32_e32 v94, 0x10000
	v_mov_b32_e32 v95, 0
	v_lshlrev_b64 v[154:155], 13, v[98:99]
	v_lshl_add_u64 v[154:155], v[92:93], 0, v[154:155]
	v_lshl_add_u64 v[156:157], v[94:95], 0, v[154:155]
	v_mul_f32_e32 v134, v126, v134
	v_mul_f32_e32 v135, v126, v135
	v_mul_f32_e32 v136, v126, v136
	v_mul_f32_e32 v137, v126, v137
	v_mul_f32_e32 v40, v126, v40
	v_mul_f32_e32 v41, v126, v41
	v_mul_f32_e32 v42, v126, v42
	v_mul_f32_e32 v43, v126, v43
	v_max_f32_e32 v134, 0, v134
	v_max_f32_e32 v135, 0, v135
	v_max_f32_e32 v136, 0, v136
	v_max_f32_e32 v137, 0, v137
	v_max_f32_e32 v40, 0, v40
	v_max_f32_e32 v41, 0, v41
	v_max_f32_e32 v42, 0, v42
	v_max_f32_e32 v43, 0, v43
	v_mul_f32_e32 v134, v134, v134
	v_mul_f32_e32 v135, v135, v135
	v_mul_f32_e32 v136, v136, v136
	v_mul_f32_e32 v137, v137, v137
	v_mul_f32_e32 v40, v40, v40
	v_mul_f32_e32 v41, v41, v41
	v_mul_f32_e32 v42, v42, v42
	v_mul_f32_e32 v43, v43, v43
	v_cvt_pk_f16_f32 v44, v134, v135
	v_cvt_pk_f16_f32 v45, v136, v137
	v_cvt_pk_f16_f32 v46, v40, v41
	v_cvt_pk_f16_f32 v47, v42, v43
	s_nop 1
	v_permlane16_swap_b32_e32 v44, v46
	v_permlane16_swap_b32_e32 v45, v47
	v_mul_f32_e32 v36, v126, v36
	v_mul_f32_e32 v37, v126, v37
	v_mul_f32_e32 v38, v126, v38
	v_mul_f32_e32 v39, v126, v39
	v_mul_f32_e32 v32, v126, v32
	v_mul_f32_e32 v33, v126, v33
	v_mul_f32_e32 v34, v126, v34
	v_mul_f32_e32 v35, v126, v35
	v_max_f32_e32 v36, 0, v36
	v_max_f32_e32 v37, 0, v37
	v_max_f32_e32 v38, 0, v38
	v_max_f32_e32 v39, 0, v39
	v_max_f32_e32 v32, 0, v32
	v_max_f32_e32 v33, 0, v33
	v_max_f32_e32 v34, 0, v34
	v_max_f32_e32 v35, 0, v35
	v_mul_f32_e32 v36, v36, v36
	v_mul_f32_e32 v37, v37, v37
	v_mul_f32_e32 v38, v38, v38
	v_mul_f32_e32 v39, v39, v39
	v_mul_f32_e32 v32, v32, v32
	v_mul_f32_e32 v33, v33, v33
	v_mul_f32_e32 v34, v34, v34
	v_mul_f32_e32 v35, v35, v35
	v_cvt_pk_f16_f32 v48, v36, v37
	v_cvt_pk_f16_f32 v49, v38, v39
	v_cvt_pk_f16_f32 v50, v32, v33
	v_cvt_pk_f16_f32 v51, v34, v35
	s_nop 1
	v_permlane16_swap_b32_e32 v48, v50
	v_permlane16_swap_b32_e32 v49, v51
	s_nop 1
	v_mov_b32_dpp v240, v44 row_ror:8 row_mask:0xf bank_mask:0x3
	v_mov_b32_dpp v241, v45 row_ror:8 row_mask:0xf bank_mask:0x3
	v_mov_b32_dpp v242, v46 row_ror:8 row_mask:0xf bank_mask:0x3
	v_mov_b32_dpp v243, v47 row_ror:8 row_mask:0xf bank_mask:0x3
	v_mov_b32_dpp v44, v48 row_ror:8 row_mask:0xf bank_mask:0xc
	v_mov_b32_dpp v45, v49 row_ror:8 row_mask:0xf bank_mask:0xc
	v_mov_b32_dpp v46, v50 row_ror:8 row_mask:0xf bank_mask:0xc
	v_mov_b32_dpp v47, v51 row_ror:8 row_mask:0xf bank_mask:0xc
	v_mov_b32_dpp v48, v240 quad_perm:[0,1,2,3] row_mask:0xf bank_mask:0x3
	v_mov_b32_dpp v49, v241 quad_perm:[0,1,2,3] row_mask:0xf bank_mask:0x3
	v_mov_b32_dpp v50, v242 quad_perm:[0,1,2,3] row_mask:0xf bank_mask:0x3
	v_mov_b32_dpp v51, v243 quad_perm:[0,1,2,3] row_mask:0xf bank_mask:0x3
	v_lshlrev_b64 v[158:159], 13, v[102:103]
	v_lshl_add_u64 v[158:159], v[92:93], 0, v[158:159]
	v_lshl_add_u64 v[160:161], v[94:95], 0, v[158:159]
	v_mul_f32_e32 v68, v128, v68
	v_mul_f32_e32 v69, v128, v69
	v_mul_f32_e32 v70, v128, v70
	v_mul_f32_e32 v71, v128, v71
	v_mul_f32_e32 v80, v128, v80
	v_mul_f32_e32 v81, v128, v81
	v_mul_f32_e32 v82, v128, v82
	v_mul_f32_e32 v83, v128, v83
	v_max_f32_e32 v68, 0, v68
	v_max_f32_e32 v69, 0, v69
	v_max_f32_e32 v70, 0, v70
	v_max_f32_e32 v71, 0, v71
	v_max_f32_e32 v80, 0, v80
	v_max_f32_e32 v81, 0, v81
	v_max_f32_e32 v82, 0, v82
	v_max_f32_e32 v83, 0, v83
	v_mul_f32_e32 v68, v68, v68
	v_mul_f32_e32 v69, v69, v69
	v_mul_f32_e32 v70, v70, v70
	v_mul_f32_e32 v71, v71, v71
	v_mul_f32_e32 v80, v80, v80
	v_mul_f32_e32 v81, v81, v81
	v_mul_f32_e32 v82, v82, v82
	v_mul_f32_e32 v83, v83, v83
; DI unsigned pack2(float lo, float hi) { f2_t v = {lo, hi}; h2_t b = __builtin_convertvector(v, h2_t); return __builtin_bit_cast(unsigned, b); }
; template <int VAR> DI void phase_up(const Params& P, int l, char* smem) {
;     ...
; #pragma unroll
;     for (int mt = 0; mt < 4; ++mt) {
;       const int row = row0 + mt * 16 + lr;
; #pragma unroll
;       for (int nt = 0; nt < 4; ++nt) {
;         float v[4];
; #pragma unroll
;         for (int j = 0; j < 4; ++j) { const float a = fmaxf(acc[mt][nt][j] * rs[mt], 0.f); v[j] = a * a; }
;         *(uint2*)(U + (size_t)row * DFF + col0 + nt * 16 + 4 * g) = make_uint2(pack2(v[0], v[1]), pack2(v[2], v[3]));
;       }
	v_cvt_pk_f16_f32 v52, v68, v69
	v_cvt_pk_f16_f32 v53, v70, v71
	v_cvt_pk_f16_f32 v54, v80, v81
	v_cvt_pk_f16_f32 v55, v82, v83
	s_nop 1
	v_permlane16_swap_b32_e32 v52, v54
	v_permlane16_swap_b32_e32 v53, v55
	v_mul_f32_e32 v84, v128, v84
	v_mul_f32_e32 v85, v128, v85
	v_mul_f32_e32 v86, v128, v86
	v_mul_f32_e32 v87, v128, v87
	v_mul_f32_e32 v130, v128, v130
	v_mul_f32_e32 v131, v128, v131
	v_mul_f32_e32 v132, v128, v132
	v_mul_f32_e32 v133, v128, v133
	v_max_f32_e32 v84, 0, v84
	v_max_f32_e32 v85, 0, v85
	v_max_f32_e32 v86, 0, v86
	v_max_f32_e32 v87, 0, v87
	v_max_f32_e32 v130, 0, v130
	v_max_f32_e32 v131, 0, v131
	v_max_f32_e32 v132, 0, v132
	v_max_f32_e32 v133, 0, v133
	v_mul_f32_e32 v84, v84, v84
	v_mul_f32_e32 v85, v85, v85
	v_mul_f32_e32 v86, v86, v86
	v_mul_f32_e32 v87, v87, v87
	v_mul_f32_e32 v130, v130, v130
	v_mul_f32_e32 v131, v131, v131
	v_mul_f32_e32 v132, v132, v132
	v_mul_f32_e32 v133, v133, v133
	v_cvt_pk_f16_f32 v56, v84, v85
	v_cvt_pk_f16_f32 v57, v86, v87
	v_cvt_pk_f16_f32 v58, v130, v131
	v_cvt_pk_f16_f32 v59, v132, v133
	s_nop 1
	v_permlane16_swap_b32_e32 v56, v58
	v_permlane16_swap_b32_e32 v57, v59
	s_nop 1
	v_mov_b32_dpp v240, v52 row_ror:8 row_mask:0xf bank_mask:0x3
	v_mov_b32_dpp v241, v53 row_ror:8 row_mask:0xf bank_mask:0x3
	v_mov_b32_dpp v242, v54 row_ror:8 row_mask:0xf bank_mask:0x3
	v_mov_b32_dpp v243, v55 row_ror:8 row_mask:0xf bank_mask:0x3
	v_mov_b32_dpp v52, v56 row_ror:8 row_mask:0xf bank_mask:0xc
	v_mov_b32_dpp v53, v57 row_ror:8 row_mask:0xf bank_mask:0xc
	v_mov_b32_dpp v54, v58 row_ror:8 row_mask:0xf bank_mask:0xc
	v_mov_b32_dpp v55, v59 row_ror:8 row_mask:0xf bank_mask:0xc
	v_mov_b32_dpp v56, v240 quad_perm:[0,1,2,3] row_mask:0xf bank_mask:0x3
	v_mov_b32_dpp v57, v241 quad_perm:[0,1,2,3] row_mask:0xf bank_mask:0x3
	v_mov_b32_dpp v58, v242 quad_perm:[0,1,2,3] row_mask:0xf bank_mask:0x3
	v_mov_b32_dpp v59, v243 quad_perm:[0,1,2,3] row_mask:0xf bank_mask:0x3
	v_lshlrev_b64 v[162:163], 13, v[106:107]
	v_lshl_add_u64 v[162:163], v[92:93], 0, v[162:163]
	v_lshl_add_u64 v[164:165], v[94:95], 0, v[162:163]
	v_mul_f32_e32 v28, v129, v28
	v_mul_f32_e32 v29, v129, v29
	v_mul_f32_e32 v30, v129, v30
	v_mul_f32_e32 v31, v129, v31
	v_mul_f32_e32 v24, v129, v24
	v_mul_f32_e32 v25, v129, v25
	v_mul_f32_e32 v26, v129, v26
	v_mul_f32_e32 v27, v129, v27
	v_max_f32_e32 v28, 0, v28
	v_max_f32_e32 v29, 0, v29
	v_max_f32_e32 v30, 0, v30
	v_max_f32_e32 v31, 0, v31
	v_max_f32_e32 v24, 0, v24
	v_max_f32_e32 v25, 0, v25
	v_max_f32_e32 v26, 0, v26
	v_max_f32_e32 v27, 0, v27
	v_mul_f32_e32 v28, v28, v28
	v_mul_f32_e32 v29, v29, v29
	v_mul_f32_e32 v30, v30, v30
	v_mul_f32_e32 v31, v31, v31
	v_mul_f32_e32 v24, v24, v24
	v_mul_f32_e32 v25, v25, v25
	v_mul_f32_e32 v26, v26, v26
	v_mul_f32_e32 v27, v27, v27
	v_cvt_pk_f16_f32 v60, v28, v29
	v_cvt_pk_f16_f32 v61, v30, v31
	v_cvt_pk_f16_f32 v62, v24, v25
	v_cvt_pk_f16_f32 v63, v26, v27
	s_nop 1
	v_permlane16_swap_b32_e32 v60, v62
	v_permlane16_swap_b32_e32 v61, v63
	v_mul_f32_e32 v20, v129, v20
	v_mul_f32_e32 v21, v129, v21
	v_mul_f32_e32 v22, v129, v22
	v_mul_f32_e32 v23, v129, v23
	v_mul_f32_e32 v16, v129, v16
	v_mul_f32_e32 v17, v129, v17
	v_mul_f32_e32 v18, v129, v18
	v_mul_f32_e32 v19, v129, v19
	v_max_f32_e32 v20, 0, v20
	v_max_f32_e32 v21, 0, v21
	v_max_f32_e32 v22, 0, v22
	v_max_f32_e32 v23, 0, v23
	v_max_f32_e32 v16, 0, v16
	v_max_f32_e32 v17, 0, v17
	v_max_f32_e32 v18, 0, v18
	v_max_f32_e32 v19, 0, v19
	v_mul_f32_e32 v20, v20, v20
	v_mul_f32_e32 v21, v21, v21
	v_mul_f32_e32 v22, v22, v22
	v_mul_f32_e32 v23, v23, v23
	v_mul_f32_e32 v16, v16, v16
	v_mul_f32_e32 v17, v17, v17
	v_mul_f32_e32 v18, v18, v18
	v_mul_f32_e32 v19, v19, v19
	v_cvt_pk_f16_f32 v32, v20, v21
	v_cvt_pk_f16_f32 v33, v22, v23
	v_cvt_pk_f16_f32 v34, v16, v17
	v_cvt_pk_f16_f32 v35, v18, v19
	s_nop 1
	v_permlane16_swap_b32_e32 v32, v34
	v_permlane16_swap_b32_e32 v33, v35
	s_nop 1
; DI unsigned pack2(float lo, float hi) { f2_t v = {lo, hi}; h2_t b = __builtin_convertvector(v, h2_t); return __builtin_bit_cast(unsigned, b); }
; template <int VAR> DI void phase_up(const Params& P, int l, char* smem) {
;     ...
; #pragma unroll
;     for (int mt = 0; mt < 4; ++mt) {
;       const int row = row0 + mt * 16 + lr;
; #pragma unroll
;       for (int nt = 0; nt < 4; ++nt) {
;         float v[4];
; #pragma unroll
;         for (int j = 0; j < 4; ++j) { const float a = fmaxf(acc[mt][nt][j] * rs[mt], 0.f); v[j] = a * a; }
;         *(uint2*)(U + (size_t)row * DFF + col0 + nt * 16 + 4 * g) = make_uint2(pack2(v[0], v[1]), pack2(v[2], v[3]));
;       }
	v_mov_b32_dpp v240, v60 row_ror:8 row_mask:0xf bank_mask:0x3
	v_mov_b32_dpp v241, v61 row_ror:8 row_mask:0xf bank_mask:0x3
	v_mov_b32_dpp v242, v62 row_ror:8 row_mask:0xf bank_mask:0x3
	v_mov_b32_dpp v243, v63 row_ror:8 row_mask:0xf bank_mask:0x3
	v_mov_b32_dpp v60, v32 row_ror:8 row_mask:0xf bank_mask:0xc
	v_mov_b32_dpp v61, v33 row_ror:8 row_mask:0xf bank_mask:0xc
	v_mov_b32_dpp v62, v34 row_ror:8 row_mask:0xf bank_mask:0xc
	v_mov_b32_dpp v63, v35 row_ror:8 row_mask:0xf bank_mask:0xc
	v_mov_b32_dpp v32, v240 quad_perm:[0,1,2,3] row_mask:0xf bank_mask:0x3
	v_mov_b32_dpp v33, v241 quad_perm:[0,1,2,3] row_mask:0xf bank_mask:0x3
	v_mov_b32_dpp v34, v242 quad_perm:[0,1,2,3] row_mask:0xf bank_mask:0x3
	v_mov_b32_dpp v35, v243 quad_perm:[0,1,2,3] row_mask:0xf bank_mask:0x3
	v_lshlrev_b64 v[166:167], 13, v[104:105]
	v_lshl_add_u64 v[166:167], v[92:93], 0, v[166:167]
	v_lshl_add_u64 v[168:169], v[94:95], 0, v[166:167]
	v_mul_f32_e32 v12, v127, v12
	v_mul_f32_e32 v13, v127, v13
	v_mul_f32_e32 v14, v127, v14
	v_mul_f32_e32 v15, v127, v15
	v_mul_f32_e32 v8, v127, v8
	v_mul_f32_e32 v9, v127, v9
	v_mul_f32_e32 v10, v127, v10
	v_mul_f32_e32 v11, v127, v11
	v_max_f32_e32 v12, 0, v12
	v_max_f32_e32 v13, 0, v13
	v_max_f32_e32 v14, 0, v14
	v_max_f32_e32 v15, 0, v15
	v_max_f32_e32 v8, 0, v8
	v_max_f32_e32 v9, 0, v9
	v_max_f32_e32 v10, 0, v10
	v_max_f32_e32 v11, 0, v11
	v_mul_f32_e32 v12, v12, v12
	v_mul_f32_e32 v13, v13, v13
	v_mul_f32_e32 v14, v14, v14
	v_mul_f32_e32 v15, v15, v15
	v_mul_f32_e32 v8, v8, v8
	v_mul_f32_e32 v9, v9, v9
	v_mul_f32_e32 v10, v10, v10
	v_mul_f32_e32 v11, v11, v11
	v_cvt_pk_f16_f32 v36, v12, v13
	v_cvt_pk_f16_f32 v37, v14, v15
	v_cvt_pk_f16_f32 v38, v8, v9
	v_cvt_pk_f16_f32 v39, v10, v11
	s_nop 1
	v_permlane16_swap_b32_e32 v36, v38
	v_permlane16_swap_b32_e32 v37, v39
	v_mul_f32_e32 v4, v127, v4
	v_mul_f32_e32 v5, v127, v5
	v_mul_f32_e32 v6, v127, v6
	v_mul_f32_e32 v7, v127, v7
	v_mul_f32_e32 v0, v127, v0
	v_mul_f32_e32 v1, v127, v1
	v_mul_f32_e32 v2, v127, v2
	v_mul_f32_e32 v3, v127, v3
	v_max_f32_e32 v4, 0, v4
	v_max_f32_e32 v5, 0, v5
	v_max_f32_e32 v6, 0, v6
	v_max_f32_e32 v7, 0, v7
	v_max_f32_e32 v0, 0, v0
	v_max_f32_e32 v1, 0, v1
	v_max_f32_e32 v2, 0, v2
	v_max_f32_e32 v3, 0, v3
	v_mul_f32_e32 v4, v4, v4
	v_mul_f32_e32 v5, v5, v5
	v_mul_f32_e32 v6, v6, v6
	v_mul_f32_e32 v7, v7, v7
	v_mul_f32_e32 v0, v0, v0
	v_mul_f32_e32 v1, v1, v1
	v_mul_f32_e32 v2, v2, v2
	v_mul_f32_e32 v3, v3, v3
	v_cvt_pk_f16_f32 v40, v4, v5
	v_cvt_pk_f16_f32 v41, v6, v7
	v_cvt_pk_f16_f32 v42, v0, v1
	v_cvt_pk_f16_f32 v43, v2, v3
	s_nop 1
	v_permlane16_swap_b32_e32 v40, v42
	v_permlane16_swap_b32_e32 v41, v43
	s_nop 1
	v_mov_b32_dpp v240, v36 row_ror:8 row_mask:0xf bank_mask:0x3
	v_mov_b32_dpp v241, v37 row_ror:8 row_mask:0xf bank_mask:0x3
	v_mov_b32_dpp v242, v38 row_ror:8 row_mask:0xf bank_mask:0x3
	v_mov_b32_dpp v243, v39 row_ror:8 row_mask:0xf bank_mask:0x3
	v_mov_b32_dpp v36, v40 row_ror:8 row_mask:0xf bank_mask:0xc
	v_mov_b32_dpp v37, v41 row_ror:8 row_mask:0xf bank_mask:0xc
	v_mov_b32_dpp v38, v42 row_ror:8 row_mask:0xf bank_mask:0xc
	v_mov_b32_dpp v39, v43 row_ror:8 row_mask:0xf bank_mask:0xc
	v_mov_b32_dpp v40, v240 quad_perm:[0,1,2,3] row_mask:0xf bank_mask:0x3
	v_mov_b32_dpp v41, v241 quad_perm:[0,1,2,3] row_mask:0xf bank_mask:0x3
	v_mov_b32_dpp v42, v242 quad_perm:[0,1,2,3] row_mask:0xf bank_mask:0x3
	v_mov_b32_dpp v43, v243 quad_perm:[0,1,2,3] row_mask:0xf bank_mask:0x3
	s_mov_b32 s100, 1
	s_branch .LBB0_1312
.LBB0_1315:
	s_cmp_eq_u32 s100, 0
	s_cbranch_scc1 .Lp6d_done
	global_store_dwordx4 v[154:155], v[44:47], off
	global_store_dwordx4 v[156:157], v[48:51], off
	global_store_dwordx4 v[158:159], v[52:55], off
	global_store_dwordx4 v[160:161], v[56:59], off
	global_store_dwordx4 v[162:163], v[60:63], off
	global_store_dwordx4 v[164:165], v[32:35], off
	global_store_dwordx4 v[166:167], v[36:39], off
	global_store_dwordx4 v[168:169], v[40:43], off
	s_mov_b32 s100, 0
